# v14
# baseline (speedup 1.0000x reference)
; template <int EPI>
; __device__ __forceinline__ void gemm_tile(const Params& p, const u16* __restrict__ A, int lda, const u16* __restrict__ Bt, int ldb,
;                                           int K, int brow, int bcol, bool prefetched, int nbrow, int nbcol, char* shm) {
;     ...
;     for (int m = 0; m < 8; ++m) {
;       const int rowb = row0 + m * 16; float g[4][4], s4[4];
; #pragma unroll
;       for (int j = 0; j < 4; ++j) {
;         const float r1 = rstd1[rowb + j]; float s = 0.f;
; #pragma unroll
;         for (int n = 0; n < 4; ++n) { g[n][j] = gelu_tanh(acc[m][n][j] * r1); s += g[n][j] * g[n][j]; }
;         s4[j] = red16(s);
.LBB0_181:
	s_or_b64 exec, exec, s[6:7]
	ds_read_b128 v[132:135], v179 offset:1024
	v_mfma_f32_16x16x32_bf16 v[108:111], v[168:171], v[152:155], v[104:107]
	v_mfma_f32_16x16x32_bf16 v[104:107], v[168:171], v[156:159], v[124:127]
	v_mfma_f32_16x16x32_bf16 v[100:103], v[168:171], v[160:163], v[100:103]
	v_mfma_f32_16x16x32_bf16 v[96:99], v[168:171], v[164:167], v[96:99]
	s_nop 0
	ds_read_b128 v[124:127], v191 offset:1024
	v_mfma_f32_16x16x32_bf16 v[92:95], v[136:139], v[152:155], v[92:95]
	v_mfma_f32_16x16x32_bf16 v[88:91], v[136:139], v[156:159], v[88:91]
	v_mfma_f32_16x16x32_bf16 v[84:87], v[136:139], v[160:163], v[84:87]
	v_mfma_f32_16x16x32_bf16 v[80:83], v[136:139], v[164:167], v[80:83]
	ds_read_b128 v[136:139], v190 offset:1024
	s_waitcnt lgkmcnt(0)
	v_mfma_f32_16x16x32_bf16 v[76:79], v[132:135], v[152:155], v[76:79]
	v_mfma_f32_16x16x32_bf16 v[72:75], v[132:135], v[156:159], v[72:75]
	v_mfma_f32_16x16x32_bf16 v[68:71], v[132:135], v[160:163], v[68:71]
	v_mfma_f32_16x16x32_bf16 v[64:67], v[132:135], v[164:167], v[64:67]
	ds_read_b128 v[132:135], v189 offset:1024
	v_mfma_f32_16x16x32_bf16 v[60:63], v[124:127], v[152:155], v[60:63]
	v_mfma_f32_16x16x32_bf16 v[56:59], v[124:127], v[156:159], v[56:59]
	v_mfma_f32_16x16x32_bf16 v[52:55], v[124:127], v[160:163], v[52:55]
	v_mfma_f32_16x16x32_bf16 v[48:51], v[124:127], v[164:167], v[48:51]
	ds_read_b128 v[124:127], v174 offset:1024
	v_mfma_f32_16x16x32_bf16 v[44:47], v[136:139], v[152:155], v[44:47]
	v_mfma_f32_16x16x32_bf16 v[40:43], v[136:139], v[156:159], v[40:43]
	v_mfma_f32_16x16x32_bf16 v[36:39], v[136:139], v[160:163], v[36:39]
	v_mfma_f32_16x16x32_bf16 v[32:35], v[136:139], v[164:167], v[32:35]
	s_waitcnt lgkmcnt(0)
	v_mfma_f32_16x16x32_bf16 v[28:31], v[132:135], v[152:155], v[28:31]
	v_mfma_f32_16x16x32_bf16 v[24:27], v[132:135], v[156:159], v[24:27]
	v_mfma_f32_16x16x32_bf16 v[20:23], v[132:135], v[160:163], v[20:23]
	v_mfma_f32_16x16x32_bf16 v[16:19], v[132:135], v[164:167], v[16:19]
	v_mfma_f32_16x16x32_bf16 v[12:15], v[124:127], v[152:155], v[12:15]
	v_mfma_f32_16x16x32_bf16 v[8:11], v[124:127], v[156:159], v[8:11]
	v_mfma_f32_16x16x32_bf16 v[4:7], v[124:127], v[160:163], v[4:7]
	v_mfma_f32_16x16x32_bf16 v[0:3], v[124:127], v[164:167], v[0:3]
	v_add_u32_e32 v124, s26, v188
	v_and_or_b32 v132, v187, 12, v124
	v_and_b32_e32 v137, 64, v217
	v_ashrrev_i32_e32 v133, 31, v132
	v_lshl_add_u64 v[134:135], v[132:133], 2, s[10:11]
	global_load_dwordx4 v[124:127], v[134:135], off
	global_load_dwordx4 v[148:151], v[134:135], off offset:64
	global_load_dwordx4 v[218:221], v[134:135], off offset:128
	global_load_dwordx4 v[222:225], v[134:135], off offset:192
	global_load_dwordx4 v[226:229], v[134:135], off offset:256
	global_load_dwordx4 v[230:233], v[134:135], off offset:320
	global_load_dwordx4 v[234:237], v[134:135], off offset:384
	global_load_dwordx4 v[240:243], v[134:135], off offset:448
	v_xor_b32_e32 v136, 1, v217
	v_add_u32_e32 v137, 64, v137
	v_xor_b32_e32 v138, 2, v217
	v_cmp_lt_i32_e32 vcc, v136, v137
	v_xor_b32_e32 v139, 4, v217
	v_xor_b32_e32 v140, 8, v217
	v_cndmask_b32_e32 v136, v217, v136, vcc
	v_cmp_lt_i32_e32 vcc, v138, v137
	v_lshlrev_b32_e32 v141, 2, v136
	s_waitcnt vmcnt(0)
	v_pk_mul_f32 v[120:121], v[120:121], v[124:125]
	v_cndmask_b32_e32 v138, v217, v138, vcc
	v_cmp_lt_i32_e32 vcc, v139, v137
	v_pk_mul_f32 v[128:129], v[128:129], v[124:125]
	v_pk_mul_f32 v[112:113], v[112:113], v[124:125]
	v_cndmask_b32_e32 v139, v217, v139, vcc
	v_cmp_lt_i32_e32 vcc, v140, v137
	v_mul_f32_e32 v144, 0x3d372713, v112
	v_mul_f32_e32 v145, 0x3d372713, v113
	v_cndmask_b32_e32 v137, v217, v140, vcc
	v_lshlrev_b32_e32 v140, 2, v138
	v_lshlrev_b32_e32 v138, 2, v137
	v_pk_mul_f32 v[136:137], v[116:117], v[124:125]
	v_pk_mul_f32 v[116:117], v[130:131], v[126:127]
	v_mul_f32_e32 v130, 0x3d372713, v120
	v_mul_f32_e32 v131, 0x3d372713, v121
	v_mul_f32_e32 v124, 0x3d372713, v128
	v_mul_f32_e32 v125, 0x3d372713, v129
	v_mul_f32_e32 v130, v120, v130
	v_mul_f32_e32 v131, v121, v131
	v_mul_f32_e32 v142, 0x3d372713, v136
	v_mul_f32_e32 v143, 0x3d372713, v137
	v_mul_f32_e32 v124, v128, v124
	v_mul_f32_e32 v125, v129, v125
	v_fma_f32 v130, v120, v130, v120
	v_fma_f32 v131, v121, v131, v121
	v_mul_f32_e32 v142, v136, v142
	v_mul_f32_e32 v143, v137, v143
	v_fma_f32 v124, v128, v124, v128
	v_fma_f32 v125, v129, v125, v129
	v_mul_f32_e32 v130, 0x3f4c422a, v130
	v_mul_f32_e32 v131, 0x3f4c422a, v131
	v_mul_f32_e32 v144, v112, v144
	v_mul_f32_e32 v145, v113, v145
	v_fma_f32 v142, v136, v142, v136
	v_fma_f32 v143, v137, v143, v137
	v_mul_f32_e32 v124, 0x3f4c422a, v124
	v_mul_f32_e32 v125, 0x3f4c422a, v125
	v_mul_f32_e32 v130, 0xc038aa3b, v130
	v_mul_f32_e32 v131, 0xc038aa3b, v131
	v_fma_f32 v144, v112, v144, v112
	v_fma_f32 v145, v113, v145, v113
	v_mul_f32_e32 v142, 0x3f4c422a, v142
	v_mul_f32_e32 v143, 0x3f4c422a, v143
	v_mul_f32_e32 v124, 0xc038aa3b, v124
	v_mul_f32_e32 v125, 0xc038aa3b, v125
	v_exp_f32_e32 v130, v130
	v_exp_f32_e32 v131, v131
	v_mul_f32_e32 v144, 0x3f4c422a, v144
	v_mul_f32_e32 v145, 0x3f4c422a, v145
	v_mul_f32_e32 v142, 0xc038aa3b, v142
	v_mul_f32_e32 v143, 0xc038aa3b, v143
	v_exp_f32_e32 v124, v124
	v_exp_f32_e32 v125, v125
	v_mul_f32_e32 v144, 0xc038aa3b, v144
	v_mul_f32_e32 v145, 0xc038aa3b, v145
	v_exp_f32_e32 v142, v142
	v_exp_f32_e32 v143, v143
	v_exp_f32_e32 v144, v144
	v_exp_f32_e32 v145, v145
	v_add_f32_e32 v130, 1.0, v130
	v_add_f32_e32 v131, 1.0, v131
	v_add_f32_e32 v124, 1.0, v124
	v_add_f32_e32 v125, 1.0, v125
	v_rcp_f32_e32 v130, v130
	v_rcp_f32_e32 v131, v131
	v_add_f32_e32 v142, 1.0, v142
	v_add_f32_e32 v143, 1.0, v143
	v_rcp_f32_e32 v124, v124
	v_rcp_f32_e32 v125, v125
	v_add_f32_e32 v144, 1.0, v144
	v_add_f32_e32 v145, 1.0, v145
	v_rcp_f32_e32 v142, v142
	v_rcp_f32_e32 v143, v143
	v_rcp_f32_e32 v144, v144
	v_rcp_f32_e32 v145, v145
	v_pk_mul_f32 v[120:121], v[120:121], v[130:131]
	v_pk_mul_f32 v[128:129], v[128:129], v[124:125]
	v_pk_mul_f32 v[130:131], v[120:121], v[120:121]
	v_pk_mul_f32 v[124:125], v[136:137], v[142:143]
	v_pk_fma_f32 v[130:131], v[128:129], v[128:129], v[130:131]
	v_pk_mul_f32 v[112:113], v[112:113], v[144:145]
	v_pk_fma_f32 v[130:131], v[124:125], v[124:125], v[130:131]
	v_mul_f32_e32 v146, 0x3d372713, v116
	v_pk_fma_f32 v[130:131], v[112:113], v[112:113], v[130:131]
	ds_bpermute_b32 v136, v141, v130
	v_mul_f32_e32 v147, 0x3d372713, v117
	v_mul_f32_e32 v146, v116, v146
	v_mul_f32_e32 v147, v117, v147
	v_fma_f32 v137, v116, v146, v116
	v_fma_f32 v142, v117, v147, v117
	v_mul_f32_e32 v137, 0x3f4c422a, v137
	v_mul_f32_e32 v142, 0x3f4c422a, v142
	s_waitcnt lgkmcnt(0)
; template <int EPI>
; __device__ __forceinline__ void gemm_tile(const Params& p, const u16* __restrict__ A, int lda, const u16* __restrict__ Bt, int ldb,
;                                           int K, int brow, int bcol, bool prefetched, int nbrow, int nbcol, char* shm) {
;     ...
;       for (int j = 0; j < 4; ++j) {
;         const float r1 = rstd1[rowb + j]; float s = 0.f;
; #pragma unroll
;         for (int n = 0; n < 4; ++n) { g[n][j] = gelu_tanh(acc[m][n][j] * r1); s += g[n][j] * g[n][j]; }
;         s4[j] = red16(s);
;       }
;       if (fr == 0) {
; #pragma unroll
;         for (int j = 0; j < 4; ++j) unsafeAtomicAdd(&ssq[rowb + j], s4[j]);
;       }
; #pragma unroll
;       for (int n = 0; n < 4; ++n) {
;         u32x2 w = {cvtpk(g[n][0], g[n][1]), cvtpk(g[n][2], g[n][3])};
;         *(u32x2*)(dst + (long)(rowb >> 7) * 131072 + (long)(cb + n * 16 + fr) * 128 + (rowb & 127)) = w;
	v_add_f32_e32 v130, v130, v136
	ds_bpermute_b32 v136, v140, v130
	v_mul_f32_e32 v137, 0xc038aa3b, v137
	v_mul_f32_e32 v142, 0xc038aa3b, v142
	v_exp_f32_e32 v137, v137
	v_exp_f32_e32 v142, v142
	s_waitcnt lgkmcnt(0)
	v_add_f32_e32 v130, v130, v136
	v_lshlrev_b32_e32 v139, 2, v139
	v_add_f32_e32 v136, 1.0, v137
	v_add_f32_e32 v137, 1.0, v142
	v_pk_mul_f32 v[142:143], v[122:123], v[126:127]
	v_rcp_f32_e32 v136, v136
	v_mul_f32_e32 v122, 0x3d372713, v142
	v_mul_f32_e32 v122, v142, v122
	v_mul_f32_e32 v123, 0x3d372713, v143
	v_fma_f32 v122, v142, v122, v142
	v_mul_f32_e32 v123, v143, v123
	v_mul_f32_e32 v122, 0x3f4c422a, v122
	v_fma_f32 v123, v143, v123, v143
	v_mul_f32_e32 v122, 0xc038aa3b, v122
	v_mul_f32_e32 v123, 0x3f4c422a, v123
	v_exp_f32_e32 v122, v122
	v_mul_f32_e32 v123, 0xc038aa3b, v123
	v_exp_f32_e32 v123, v123
	v_rcp_f32_e32 v137, v137
	v_add_f32_e32 v122, 1.0, v122
	v_rcp_f32_e32 v144, v122
	v_add_f32_e32 v122, 1.0, v123
	v_rcp_f32_e32 v145, v122
	v_pk_mul_f32 v[122:123], v[116:117], v[136:137]
	v_pk_mul_f32 v[116:117], v[118:119], v[126:127]
	v_pk_mul_f32 v[126:127], v[114:115], v[126:127]
	v_mul_f32_e32 v118, 0x3d372713, v116
	v_mul_f32_e32 v118, v116, v118
	v_fma_f32 v118, v116, v118, v116
	v_mul_f32_e32 v118, 0x3f4c422a, v118
	v_mul_f32_e32 v118, 0xc038aa3b, v118
	v_pk_mul_f32 v[136:137], v[142:143], v[144:145]
	v_exp_f32_e32 v142, v118
	v_mul_f32_e32 v118, 0x3d372713, v117
	v_mul_f32_e32 v114, 0x3d372713, v126
	v_mul_f32_e32 v118, v117, v118
	v_mul_f32_e32 v114, v126, v114
	v_mul_f32_e32 v115, 0x3d372713, v127
	v_fma_f32 v118, v117, v118, v117
	v_fma_f32 v114, v126, v114, v126
	v_mul_f32_e32 v115, v127, v115
	v_mul_f32_e32 v118, 0x3f4c422a, v118
	v_mul_f32_e32 v114, 0x3f4c422a, v114
	v_fma_f32 v115, v127, v115, v127
	v_mul_f32_e32 v118, 0xc038aa3b, v118
	v_mul_f32_e32 v114, 0xc038aa3b, v114
	v_mul_f32_e32 v115, 0x3f4c422a, v115
	v_exp_f32_e32 v143, v118
	v_exp_f32_e32 v114, v114
	v_mul_f32_e32 v115, 0xc038aa3b, v115
	v_exp_f32_e32 v115, v115
	v_add_f32_e32 v142, 1.0, v142
	v_add_f32_e32 v143, 1.0, v143
	v_add_f32_e32 v114, 1.0, v114
	v_rcp_f32_e32 v142, v142
	v_rcp_f32_e32 v143, v143
	v_rcp_f32_e32 v144, v114
	v_add_f32_e32 v114, 1.0, v115
	v_rcp_f32_e32 v145, v114
	ds_bpermute_b32 v146, v139, v130
	v_pk_mul_f32 v[118:119], v[136:137], v[136:137]
	v_pk_mul_f32 v[114:115], v[116:117], v[142:143]
	v_pk_fma_f32 v[118:119], v[122:123], v[122:123], v[118:119]
	v_pk_mul_f32 v[126:127], v[126:127], v[144:145]
	v_pk_fma_f32 v[116:117], v[114:115], v[114:115], v[118:119]
	s_waitcnt lgkmcnt(0)
	v_add_f32_e32 v130, v130, v146
	v_pk_fma_f32 v[116:117], v[126:127], v[126:127], v[116:117]
	ds_bpermute_b32 v146, v141, v131
	ds_bpermute_b32 v119, v141, v116
	ds_bpermute_b32 v142, v141, v117
	ds_bpermute_b32 v118, v138, v130
	v_cmp_eq_u32_e32 vcc, 0, v181
	s_waitcnt lgkmcnt(3)
	v_add_f32_e32 v131, v131, v146
	s_waitcnt lgkmcnt(2)
	v_add_f32_e32 v116, v116, v119
	s_waitcnt lgkmcnt(1)
	v_add_f32_e32 v117, v117, v142
	ds_bpermute_b32 v143, v140, v131
	ds_bpermute_b32 v119, v140, v116
	ds_bpermute_b32 v142, v140, v117
	s_waitcnt lgkmcnt(2)
	v_add_f32_e32 v131, v131, v143
	s_waitcnt lgkmcnt(1)
	v_add_f32_e32 v116, v116, v119
	s_waitcnt lgkmcnt(0)
	v_add_f32_e32 v117, v117, v142
	ds_bpermute_b32 v143, v139, v131
	ds_bpermute_b32 v144, v139, v116
	ds_bpermute_b32 v145, v139, v117
	s_waitcnt lgkmcnt(2)
	v_add_f32_e32 v119, v131, v143
	s_waitcnt lgkmcnt(1)
	v_add_f32_e32 v142, v116, v144
	s_waitcnt lgkmcnt(0)
	v_add_f32_e32 v144, v117, v145
	ds_bpermute_b32 v131, v138, v119
	ds_bpermute_b32 v143, v138, v142
	ds_bpermute_b32 v145, v138, v144
	v_lshl_add_u64 v[116:117], v[132:133], 2, s[16:17]
	s_and_saveexec_b64 s[6:7], vcc
	s_cbranch_execz .LBB0_183
	v_add_f32_e32 v118, v130, v118
	s_waitcnt lgkmcnt(0)
	v_add_f32_e32 v133, v144, v145
	v_add_f32_e32 v142, v142, v143
	v_add_f32_e32 v119, v119, v131
	global_atomic_add_f32 v[116:117], v118, off
	global_atomic_add_f32 v[116:117], v119, off offset:4
	global_atomic_add_f32 v[116:117], v142, off offset:8
	global_atomic_add_f32 v[116:117], v133, off offset:12
.LBB0_183:
	s_or_b64 exec, exec, s[6:7]
	v_lshlrev_b32_e32 v118, 6, v180
	s_add_i32 s6, s24, 0xfffff900
	v_or3_b32 v130, v118, s6, v181
	v_ashrrev_i32_e32 v118, 7, v132
	v_ashrrev_i32_e32 v119, 31, v118
	v_lshlrev_b64 v[118:119], 18, v[118:119]
	s_waitcnt lgkmcnt(2)
	v_and_b32_e32 v131, 0x7f, v132
	v_lshl_add_u64 v[118:119], s[14:15], 0, v[118:119]
	v_lshlrev_b32_e32 v204, 1, v131
	v_mov_b32_e32 v131, v205
	s_waitcnt lgkmcnt(1)
; template <int EPI>
; __device__ __forceinline__ void gemm_tile(const Params& p, const u16* __restrict__ A, int lda, const u16* __restrict__ Bt, int ldb,
;                                           int K, int brow, int bcol, bool prefetched, int nbrow, int nbcol, char* shm) {
;     ...
;     for (int m = 0; m < 8; ++m) {
;       const int rowb = row0 + m * 16; float g[4][4], s4[4];
; #pragma unroll
;       for (int j = 0; j < 4; ++j) {
;         const float r1 = rstd1[rowb + j]; float s = 0.f;
; #pragma unroll
;         for (int n = 0; n < 4; ++n) { g[n][j] = gelu_tanh(acc[m][n][j] * r1); s += g[n][j] * g[n][j]; }
;     ...
; #pragma unroll
;       for (int n = 0; n < 4; ++n) {
;         u32x2 w = {cvtpk(g[n][0], g[n][1]), cvtpk(g[n][2], g[n][3])};
;         *(u32x2*)(dst + (long)(rowb >> 7) * 131072 + (long)(cb + n * 16 + fr) * 128 + (rowb & 127)) = w;
;       }
	v_lshl_add_u64 v[142:143], v[118:119], 0, v[204:205]
	v_lshlrev_b64 v[118:119], 8, v[130:131]
	v_cvt_pk_bf16_f32 v128, v128, v129
	v_cvt_pk_bf16_f32 v129, v122, v123
	v_lshl_add_u64 v[122:123], v[142:143], 0, v[118:119]
	v_or_b32_e32 v204, 16, v130
	global_store_dwordx2 v[122:123], v[128:129], off
	v_cvt_pk_bf16_f32 v122, v120, v121
	v_lshlrev_b64 v[120:121], 8, v[204:205]
	v_cvt_pk_bf16_f32 v123, v136, v137
	v_lshl_add_u64 v[128:129], v[142:143], 0, v[120:121]
	v_or_b32_e32 v204, 32, v130
	global_store_dwordx2 v[128:129], v[122:123], off
	v_lshlrev_b64 v[122:123], 8, v[204:205]
	v_cvt_pk_bf16_f32 v124, v124, v125
	v_cvt_pk_bf16_f32 v125, v114, v115
	v_lshl_add_u64 v[114:115], v[142:143], 0, v[122:123]
	v_or_b32_e32 v204, 48, v130
	global_store_dwordx2 v[114:115], v[124:125], off
	v_lshlrev_b64 v[124:125], 8, v[204:205]
	v_cvt_pk_bf16_f32 v112, v112, v113
	v_cvt_pk_bf16_f32 v113, v126, v127
	v_lshl_add_u64 v[114:115], v[142:143], 0, v[124:125]
	global_store_dwordx2 v[114:115], v[112:113], off
	s_nop 1
	v_mov_b64_e32 v[112:113], v[148:149]
	v_mov_b64_e32 v[114:115], v[150:151]
	v_pk_mul_f32 v[126:127], v[104:105], v[112:113]
	v_pk_mul_f32 v[108:109], v[108:109], v[112:113]
	v_pk_mul_f32 v[128:129], v[100:101], v[112:113]
	v_mul_f32_e32 v100, 0x3d372713, v126
	v_mul_f32_e32 v101, 0x3d372713, v127
	v_pk_mul_f32 v[112:113], v[96:97], v[112:113]
	v_mul_f32_e32 v96, 0x3d372713, v108
	v_mul_f32_e32 v97, 0x3d372713, v109
	v_mul_f32_e32 v100, v126, v100
	v_mul_f32_e32 v101, v127, v101
	v_mul_f32_e32 v104, 0x3d372713, v128
	v_mul_f32_e32 v105, 0x3d372713, v129
	v_mul_f32_e32 v96, v108, v96
	v_mul_f32_e32 v97, v109, v97
	v_fma_f32 v100, v126, v100, v126
	v_fma_f32 v101, v127, v101, v127
	v_mul_f32_e32 v130, 0x3d372713, v112
	v_mul_f32_e32 v131, 0x3d372713, v113
	v_mul_f32_e32 v104, v128, v104
	v_mul_f32_e32 v105, v129, v105
	v_fma_f32 v96, v108, v96, v108
	v_fma_f32 v97, v109, v97, v109
	v_mul_f32_e32 v100, 0x3f4c422a, v100
	v_mul_f32_e32 v101, 0x3f4c422a, v101
	v_mul_f32_e32 v130, v112, v130
	v_mul_f32_e32 v131, v113, v131
	v_fma_f32 v104, v128, v104, v128
	v_fma_f32 v105, v129, v105, v129
	v_mul_f32_e32 v96, 0x3f4c422a, v96
	v_mul_f32_e32 v97, 0x3f4c422a, v97
	v_mul_f32_e32 v100, 0xc038aa3b, v100
	v_mul_f32_e32 v101, 0xc038aa3b, v101
	v_fma_f32 v130, v112, v130, v112
	v_fma_f32 v131, v113, v131, v113
	v_mul_f32_e32 v104, 0x3f4c422a, v104
	v_mul_f32_e32 v105, 0x3f4c422a, v105
	v_mul_f32_e32 v96, 0xc038aa3b, v96
	v_mul_f32_e32 v97, 0xc038aa3b, v97
	v_exp_f32_e32 v100, v100
	v_exp_f32_e32 v101, v101
	v_mul_f32_e32 v130, 0x3f4c422a, v130
	v_mul_f32_e32 v131, 0x3f4c422a, v131
	v_mul_f32_e32 v104, 0xc038aa3b, v104
	v_mul_f32_e32 v105, 0xc038aa3b, v105
	v_exp_f32_e32 v96, v96
	v_exp_f32_e32 v97, v97
	v_mul_f32_e32 v130, 0xc038aa3b, v130
	v_mul_f32_e32 v131, 0xc038aa3b, v131
	v_exp_f32_e32 v104, v104
	v_exp_f32_e32 v105, v105
	v_exp_f32_e32 v130, v130
	v_exp_f32_e32 v131, v131
	v_add_f32_e32 v100, 1.0, v100
	v_add_f32_e32 v101, 1.0, v101
	v_add_f32_e32 v96, 1.0, v96
	v_add_f32_e32 v97, 1.0, v97
	v_rcp_f32_e32 v100, v100
	v_rcp_f32_e32 v101, v101
	v_add_f32_e32 v104, 1.0, v104
	v_add_f32_e32 v105, 1.0, v105
	v_rcp_f32_e32 v96, v96
	v_rcp_f32_e32 v97, v97
	v_add_f32_e32 v133, 1.0, v130
	v_add_f32_e32 v137, 1.0, v131
	v_rcp_f32_e32 v130, v104
	v_rcp_f32_e32 v131, v105
	v_rcp_f32_e32 v136, v133
	v_rcp_f32_e32 v137, v137
	v_pk_mul_f32 v[100:101], v[126:127], v[100:101]
	v_pk_mul_f32 v[104:105], v[108:109], v[96:97]
	v_pk_mul_f32 v[108:109], v[100:101], v[100:101]
	v_pk_mul_f32 v[96:97], v[128:129], v[130:131]
	v_pk_fma_f32 v[108:109], v[104:105], v[104:105], v[108:109]
	v_pk_mul_f32 v[110:111], v[110:111], v[114:115]
	v_pk_fma_f32 v[126:127], v[96:97], v[96:97], v[108:109]
	v_pk_mul_f32 v[108:109], v[112:113], v[136:137]
	v_pk_mul_f32 v[130:131], v[106:107], v[114:115]
	v_pk_fma_f32 v[112:113], v[108:109], v[108:109], v[126:127]
	ds_bpermute_b32 v126, v141, v112
	v_mul_f32_e32 v127, 0x3d372713, v110
	v_mul_f32_e32 v127, v110, v127
	v_fma_f32 v127, v110, v127, v110
	v_mul_f32_e32 v127, 0x3f4c422a, v127
	s_waitcnt lgkmcnt(0)
	v_add_f32_e32 v112, v112, v126
	ds_bpermute_b32 v126, v140, v112
	v_mul_f32_e32 v106, 0x3d372713, v130
	v_mul_f32_e32 v127, 0xc038aa3b, v127
	v_mul_f32_e32 v106, v130, v106
	v_mul_f32_e32 v107, 0x3d372713, v131
	s_waitcnt lgkmcnt(0)
	v_add_f32_e32 v112, v112, v126
	v_mul_f32_e32 v126, 0x3d372713, v111
	v_mul_f32_e32 v126, v111, v126
	v_fma_f32 v126, v111, v126, v111
	v_mul_f32_e32 v126, 0x3f4c422a, v126
	v_mul_f32_e32 v126, 0xc038aa3b, v126
	v_exp_f32_e32 v127, v127
	v_exp_f32_e32 v126, v126
	v_fma_f32 v106, v130, v106, v130
	v_mul_f32_e32 v107, v131, v107
	v_mul_f32_e32 v106, 0x3f4c422a, v106
	v_fma_f32 v107, v131, v107, v131
	v_mul_f32_e32 v106, 0xc038aa3b, v106
	v_mul_f32_e32 v107, 0x3f4c422a, v107
	v_exp_f32_e32 v106, v106
	v_mul_f32_e32 v107, 0xc038aa3b, v107
	v_add_f32_e32 v127, 1.0, v127
	v_add_f32_e32 v126, 1.0, v126
	v_exp_f32_e32 v107, v107
	v_rcp_f32_e32 v128, v127
	v_rcp_f32_e32 v129, v126
	v_add_f32_e32 v106, 1.0, v106
	v_pk_mul_f32 v[102:103], v[102:103], v[114:115]
	v_rcp_f32_e32 v136, v106
	v_add_f32_e32 v106, 1.0, v107
	v_mul_f32_e32 v127, 0x3d372713, v102
	v_pk_mul_f32 v[114:115], v[98:99], v[114:115]
	v_rcp_f32_e32 v137, v106
	v_pk_mul_f32 v[106:107], v[110:111], v[128:129]
	v_mul_f32_e32 v127, v102, v127
	v_mul_f32_e32 v128, 0x3d372713, v103
	v_mul_f32_e32 v98, 0x3d372713, v114
	v_fma_f32 v127, v102, v127, v102
	v_mul_f32_e32 v128, v103, v128
	v_mul_f32_e32 v98, v114, v98
	v_mul_f32_e32 v99, 0x3d372713, v115
	v_mul_f32_e32 v127, 0x3f4c422a, v127
	v_fma_f32 v128, v103, v128, v103
	v_fma_f32 v98, v114, v98, v114
	v_mul_f32_e32 v99, v115, v99
	v_mul_f32_e32 v127, 0xc038aa3b, v127
	v_mul_f32_e32 v128, 0x3f4c422a, v128
	v_mul_f32_e32 v98, 0x3f4c422a, v98
	v_fma_f32 v99, v115, v99, v115
	v_exp_f32_e32 v127, v127
	v_mul_f32_e32 v128, 0xc038aa3b, v128
	v_mul_f32_e32 v98, 0xc038aa3b, v98
	v_mul_f32_e32 v99, 0x3f4c422a, v99
	v_pk_mul_f32 v[110:111], v[130:131], v[136:137]
	v_exp_f32_e32 v131, v128
	v_exp_f32_e32 v98, v98
	v_mul_f32_e32 v99, 0xc038aa3b, v99
	v_exp_f32_e32 v99, v99
	v_add_f32_e32 v127, 1.0, v127
	v_rcp_f32_e32 v130, v127
	v_add_f32_e32 v127, 1.0, v131
	v_add_f32_e32 v98, 1.0, v98
	v_rcp_f32_e32 v131, v127
	v_rcp_f32_e32 v136, v98
	v_add_f32_e32 v98, 1.0, v99
	v_rcp_f32_e32 v137, v98
	ds_bpermute_b32 v133, v139, v112
	v_pk_mul_f32 v[128:129], v[110:111], v[110:111]
	v_pk_mul_f32 v[98:99], v[102:103], v[130:131]
	v_pk_fma_f32 v[128:129], v[106:107], v[106:107], v[128:129]
	v_pk_mul_f32 v[102:103], v[114:115], v[136:137]
	v_pk_fma_f32 v[128:129], v[98:99], v[98:99], v[128:129]
	s_waitcnt lgkmcnt(0)
; template <int EPI>
; __device__ __forceinline__ void gemm_tile(const Params& p, const u16* __restrict__ A, int lda, const u16* __restrict__ Bt, int ldb,
;                                           int K, int brow, int bcol, bool prefetched, int nbrow, int nbcol, char* shm) {
;     ...
;       for (int j = 0; j < 4; ++j) {
;         const float r1 = rstd1[rowb + j]; float s = 0.f;
; #pragma unroll
;         for (int n = 0; n < 4; ++n) { g[n][j] = gelu_tanh(acc[m][n][j] * r1); s += g[n][j] * g[n][j]; }
;         s4[j] = red16(s);
;       }
;       if (fr == 0) {
; #pragma unroll
;         for (int j = 0; j < 4; ++j) unsafeAtomicAdd(&ssq[rowb + j], s4[j]);
;       }
; #pragma unroll
;       for (int n = 0; n < 4; ++n) {
;         u32x2 w = {cvtpk(g[n][0], g[n][1]), cvtpk(g[n][2], g[n][3])};
;         *(u32x2*)(dst + (long)(rowb >> 7) * 131072 + (long)(cb + n * 16 + fr) * 128 + (rowb & 127)) = w;
;       }
	v_add_f32_e32 v126, v112, v133
	v_pk_fma_f32 v[128:129], v[102:103], v[102:103], v[128:129]
	ds_bpermute_b32 v112, v141, v113
	ds_bpermute_b32 v115, v141, v128
	ds_bpermute_b32 v127, v141, v129
	ds_bpermute_b32 v114, v138, v126
	s_waitcnt lgkmcnt(3)
	v_add_f32_e32 v112, v113, v112
	s_waitcnt lgkmcnt(2)
	v_add_f32_e32 v115, v128, v115
	s_waitcnt lgkmcnt(1)
	v_add_f32_e32 v127, v129, v127
	ds_bpermute_b32 v113, v140, v112
	ds_bpermute_b32 v128, v140, v115
	ds_bpermute_b32 v129, v140, v127
	s_waitcnt lgkmcnt(2)
	v_add_f32_e32 v112, v112, v113
	s_waitcnt lgkmcnt(1)
	v_add_f32_e32 v128, v115, v128
	s_waitcnt lgkmcnt(0)
	v_add_f32_e32 v131, v127, v129
	ds_bpermute_b32 v113, v139, v112
	ds_bpermute_b32 v130, v139, v128
	ds_bpermute_b32 v133, v139, v131
	s_waitcnt lgkmcnt(2)
	v_add_f32_e32 v115, v112, v113
	s_waitcnt lgkmcnt(1)
	v_add_f32_e32 v128, v128, v130
	s_waitcnt lgkmcnt(0)
	v_add_f32_e32 v130, v131, v133
	ds_bpermute_b32 v127, v138, v115
	ds_bpermute_b32 v129, v138, v128
	ds_bpermute_b32 v131, v138, v130
	v_add_u32_e32 v112, 16, v132
	v_ashrrev_i32_e32 v113, 31, v112
	s_and_saveexec_b64 s[6:7], vcc
	s_cbranch_execz .LBB0_185
	s_waitcnt lgkmcnt(2)
	v_add_f32_e32 v127, v115, v127
	v_add_f32_e32 v126, v126, v114
	v_lshl_add_u64 v[114:115], v[112:113], 2, s[16:17]
	s_waitcnt lgkmcnt(0)
	v_add_f32_e32 v130, v130, v131
	v_add_f32_e32 v128, v128, v129
	global_atomic_add_f32 v[114:115], v126, off
	global_atomic_add_f32 v[116:117], v127, off offset:68
	global_atomic_add_f32 v[116:117], v128, off offset:72
	global_atomic_add_f32 v[116:117], v130, off offset:76
.LBB0_185:
	s_or_b64 exec, exec, s[6:7]
	v_ashrrev_i32_e32 v114, 7, v112
	v_ashrrev_i32_e32 v115, 31, v114
	v_lshlrev_b64 v[114:115], 18, v[114:115]
	v_and_b32_e32 v112, 0x7f, v112
	v_lshl_add_u64 v[114:115], s[14:15], 0, v[114:115]
	v_lshlrev_b32_e32 v204, 1, v112
	v_lshl_add_u64 v[112:113], v[114:115], 0, v[204:205]
	v_cvt_pk_bf16_f32 v104, v104, v105
	v_cvt_pk_bf16_f32 v105, v106, v107
	v_lshl_add_u64 v[106:107], v[112:113], 0, v[118:119]
	v_cvt_pk_bf16_f32 v96, v96, v97
	v_cvt_pk_bf16_f32 v97, v98, v99
	v_lshl_add_u64 v[98:99], v[112:113], 0, v[122:123]
	global_store_dwordx2 v[106:107], v[104:105], off
	v_cvt_pk_bf16_f32 v100, v100, v101
	v_cvt_pk_bf16_f32 v101, v110, v111
	v_lshl_add_u64 v[104:105], v[112:113], 0, v[120:121]
	global_store_dwordx2 v[98:99], v[96:97], off
	v_cvt_pk_bf16_f32 v96, v108, v109
	v_cvt_pk_bf16_f32 v97, v102, v103
	v_lshl_add_u64 v[98:99], v[112:113], 0, v[124:125]
	global_store_dwordx2 v[104:105], v[100:101], off
	global_store_dwordx2 v[98:99], v[96:97], off
	s_nop 1
	v_mov_b64_e32 v[96:97], v[218:219]
	v_mov_b64_e32 v[98:99], v[220:221]
	v_pk_mul_f32 v[88:89], v[88:89], v[96:97]
	v_pk_mul_f32 v[84:85], v[84:85], v[96:97]
	v_mul_f32_e32 v100, 0x3d372713, v88
	v_mul_f32_e32 v101, 0x3d372713, v89
	v_mul_f32_e32 v102, 0x3d372713, v84
	v_mul_f32_e32 v103, 0x3d372713, v85
	v_mul_f32_e32 v100, v88, v100
	v_mul_f32_e32 v101, v89, v101
	v_mul_f32_e32 v102, v84, v102
	v_mul_f32_e32 v103, v85, v103
	v_fma_f32 v100, v88, v100, v88
	v_fma_f32 v101, v89, v101, v89
	v_fma_f32 v102, v84, v102, v84
	v_fma_f32 v103, v85, v103, v85
	v_mul_f32_e32 v100, 0x3f4c422a, v100
	v_mul_f32_e32 v101, 0x3f4c422a, v101
	v_mul_f32_e32 v102, 0x3f4c422a, v102
	v_mul_f32_e32 v103, 0x3f4c422a, v103
	v_mul_f32_e32 v100, 0xc038aa3b, v100
	v_mul_f32_e32 v101, 0xc038aa3b, v101
	v_mul_f32_e32 v102, 0xc038aa3b, v102
	v_mul_f32_e32 v103, 0xc038aa3b, v103
	v_exp_f32_e32 v100, v100
	v_exp_f32_e32 v101, v101
	v_exp_f32_e32 v102, v102
	v_exp_f32_e32 v103, v103
	v_add_f32_e32 v100, 1.0, v100
	v_add_f32_e32 v101, 1.0, v101
	v_pk_mul_f32 v[94:95], v[94:95], v[98:99]
	v_add_f32_e32 v102, 1.0, v102
	v_add_f32_e32 v103, 1.0, v103
	v_rcp_f32_e32 v100, v100
	v_rcp_f32_e32 v101, v101
	v_pk_mul_f32 v[80:81], v[80:81], v[96:97]
	v_mul_f32_e32 v106, 0x3d372713, v94
	v_rcp_f32_e32 v102, v102
	v_rcp_f32_e32 v103, v103
	v_mul_f32_e32 v104, 0x3d372713, v80
	v_mul_f32_e32 v105, 0x3d372713, v81
	v_mul_f32_e32 v107, 0x3d372713, v95
	v_mul_f32_e32 v106, v94, v106
	v_mul_f32_e32 v104, v80, v104
	v_mul_f32_e32 v105, v81, v105
	v_mul_f32_e32 v107, v95, v107
	v_fma_f32 v106, v94, v106, v94
	v_fma_f32 v104, v80, v104, v80
	v_fma_f32 v105, v81, v105, v81
	v_fma_f32 v107, v95, v107, v95
	v_pk_mul_f32 v[88:89], v[88:89], v[100:101]
	v_mul_f32_e32 v101, 0x3f4c422a, v106
	v_mul_f32_e32 v104, 0x3f4c422a, v104
	v_mul_f32_e32 v105, 0x3f4c422a, v105
	v_pk_mul_f32 v[84:85], v[84:85], v[102:103]
	v_mul_f32_e32 v102, 0x3f4c422a, v107
	v_mul_f32_e32 v101, 0xc038aa3b, v101
	v_mul_f32_e32 v104, 0xc038aa3b, v104
	v_mul_f32_e32 v105, 0xc038aa3b, v105
	v_exp_f32_e32 v101, v101
	v_mul_f32_e32 v102, 0xc038aa3b, v102
	v_exp_f32_e32 v104, v104
	v_exp_f32_e32 v105, v105
	v_exp_f32_e32 v103, v102
	v_pk_mul_f32 v[92:93], v[92:93], v[96:97]
	v_add_f32_e32 v101, 1.0, v101
	v_mul_f32_e32 v96, 0x3d372713, v92
	v_mul_f32_e32 v97, 0x3d372713, v93
	v_mul_f32_e32 v96, v92, v96
	v_mul_f32_e32 v97, v93, v97
	v_pk_mul_f32 v[90:91], v[90:91], v[98:99]
	v_fma_f32 v96, v92, v96, v92
	v_fma_f32 v97, v93, v97, v93
	v_add_f32_e32 v104, 1.0, v104
	v_add_f32_e32 v105, 1.0, v105
	v_rcp_f32_e32 v102, v101
	v_add_f32_e32 v101, 1.0, v103
	v_mul_f32_e32 v103, 0x3d372713, v90
	v_mul_f32_e32 v96, 0x3f4c422a, v96
	v_mul_f32_e32 v97, 0x3f4c422a, v97
	v_rcp_f32_e32 v104, v104
	v_rcp_f32_e32 v105, v105
	v_mul_f32_e32 v103, v90, v103
	v_mul_f32_e32 v96, 0xc038aa3b, v96
	v_mul_f32_e32 v97, 0xc038aa3b, v97
	v_fma_f32 v103, v90, v103, v90
	v_exp_f32_e32 v96, v96
	v_exp_f32_e32 v97, v97
	v_mul_f32_e32 v103, 0x3f4c422a, v103
	v_mul_f32_e32 v103, 0xc038aa3b, v103
	v_pk_mul_f32 v[80:81], v[80:81], v[104:105]
; template <int EPI>
; __device__ __forceinline__ void gemm_tile(const Params& p, const u16* __restrict__ A, int lda, const u16* __restrict__ Bt, int ldb,
;                                           int K, int brow, int bcol, bool prefetched, int nbrow, int nbcol, char* shm) {
;     ...
;       for (int j = 0; j < 4; ++j) {
;         const float r1 = rstd1[rowb + j]; float s = 0.f;
; #pragma unroll
;         for (int n = 0; n < 4; ++n) { g[n][j] = gelu_tanh(acc[m][n][j] * r1); s += g[n][j] * g[n][j]; }
;         s4[j] = red16(s);
;       }
;       if (fr == 0) {
; #pragma unroll
;         for (int j = 0; j < 4; ++j) unsafeAtomicAdd(&ssq[rowb + j], s4[j]);
;       }
; #pragma unroll
;       for (int n = 0; n < 4; ++n) {
;         u32x2 w = {cvtpk(g[n][0], g[n][1]), cvtpk(g[n][2], g[n][3])};
;         *(u32x2*)(dst + (long)(rowb >> 7) * 131072 + (long)(cb + n * 16 + fr) * 128 + (rowb & 127)) = w;
;       }
	v_exp_f32_e32 v104, v103
	v_mul_f32_e32 v103, 0x3d372713, v91
	v_mul_f32_e32 v103, v91, v103
	v_add_f32_e32 v96, 1.0, v96
	v_add_f32_e32 v97, 1.0, v97
	v_fma_f32 v103, v91, v103, v91
	v_rcp_f32_e32 v96, v96
	v_rcp_f32_e32 v97, v97
	v_mul_f32_e32 v103, 0x3f4c422a, v103
	v_mul_f32_e32 v103, 0xc038aa3b, v103
	v_exp_f32_e32 v105, v103
	v_pk_mul_f32 v[92:93], v[92:93], v[96:97]
	v_pk_mul_f32 v[96:97], v[88:89], v[88:89]
	v_rcp_f32_e32 v103, v101
	v_pk_fma_f32 v[96:97], v[92:93], v[92:93], v[96:97]
	v_add_f32_e32 v101, 1.0, v104
	v_pk_fma_f32 v[96:97], v[84:85], v[84:85], v[96:97]
	v_rcp_f32_e32 v104, v101
	v_add_f32_e32 v101, 1.0, v105
	v_pk_mul_f32 v[86:87], v[86:87], v[98:99]
	v_pk_fma_f32 v[96:97], v[80:81], v[80:81], v[96:97]
	v_rcp_f32_e32 v105, v101
	v_mul_f32_e32 v101, 0x3d372713, v86
	ds_bpermute_b32 v100, v141, v96
	v_pk_mul_f32 v[94:95], v[94:95], v[102:103]
	v_mul_f32_e32 v101, v86, v101
	v_mul_f32_e32 v102, 0x3d372713, v87
	v_pk_mul_f32 v[82:83], v[82:83], v[98:99]
	v_fma_f32 v101, v86, v101, v86
	v_mul_f32_e32 v102, v87, v102
	v_mul_f32_e32 v98, 0x3d372713, v82
	v_mul_f32_e32 v99, 0x3d372713, v83
	v_mul_f32_e32 v101, 0x3f4c422a, v101
	v_fma_f32 v102, v87, v102, v87
	v_mul_f32_e32 v98, v82, v98
	v_mul_f32_e32 v99, v83, v99
	v_mul_f32_e32 v101, 0xc038aa3b, v101
	v_mul_f32_e32 v102, 0x3f4c422a, v102
	v_fma_f32 v98, v82, v98, v82
	v_fma_f32 v99, v83, v99, v83
	v_exp_f32_e32 v101, v101
	v_mul_f32_e32 v102, 0xc038aa3b, v102
	v_mul_f32_e32 v98, 0x3f4c422a, v98
	v_mul_f32_e32 v99, 0x3f4c422a, v99
	s_waitcnt lgkmcnt(0)
	v_add_f32_e32 v96, v96, v100
	v_pk_mul_f32 v[90:91], v[90:91], v[104:105]
	v_exp_f32_e32 v105, v102
	v_mul_f32_e32 v98, 0xc038aa3b, v98
	v_mul_f32_e32 v99, 0xc038aa3b, v99
	ds_bpermute_b32 v100, v140, v96
	v_exp_f32_e32 v98, v98
	v_exp_f32_e32 v99, v99
	v_add_f32_e32 v101, 1.0, v101
	v_rcp_f32_e32 v104, v101
	v_add_f32_e32 v101, 1.0, v105
	v_rcp_f32_e32 v105, v101
	v_add_f32_e32 v98, 1.0, v98
	v_add_f32_e32 v99, 1.0, v99
	s_waitcnt lgkmcnt(0)
	v_add_f32_e32 v96, v96, v100
	v_rcp_f32_e32 v98, v98
	v_rcp_f32_e32 v99, v99
	ds_bpermute_b32 v100, v139, v96
	v_pk_mul_f32 v[102:103], v[90:91], v[90:91]
	v_pk_mul_f32 v[86:87], v[86:87], v[104:105]
	v_pk_fma_f32 v[102:103], v[94:95], v[94:95], v[102:103]
	v_pk_mul_f32 v[82:83], v[82:83], v[98:99]
	v_pk_fma_f32 v[102:103], v[86:87], v[86:87], v[102:103]
	s_waitcnt lgkmcnt(0)
	v_add_f32_e32 v100, v96, v100
	v_pk_fma_f32 v[102:103], v[82:83], v[82:83], v[102:103]
	ds_bpermute_b32 v96, v141, v97
	ds_bpermute_b32 v99, v141, v102
	ds_bpermute_b32 v101, v141, v103
	ds_bpermute_b32 v98, v138, v100
	s_waitcnt lgkmcnt(3)
	v_add_f32_e32 v96, v97, v96
	s_waitcnt lgkmcnt(2)
	v_add_f32_e32 v99, v102, v99
	s_waitcnt lgkmcnt(1)
	v_add_f32_e32 v101, v103, v101
	ds_bpermute_b32 v97, v140, v96
	ds_bpermute_b32 v102, v140, v99
	ds_bpermute_b32 v103, v140, v101
	s_waitcnt lgkmcnt(2)
	v_add_f32_e32 v96, v96, v97
	s_waitcnt lgkmcnt(1)
	v_add_f32_e32 v102, v99, v102
	s_waitcnt lgkmcnt(0)
	v_add_f32_e32 v105, v101, v103
	ds_bpermute_b32 v97, v139, v96
	ds_bpermute_b32 v104, v139, v102
	ds_bpermute_b32 v106, v139, v105
	s_waitcnt lgkmcnt(2)
	v_add_f32_e32 v99, v96, v97
	s_waitcnt lgkmcnt(1)
	v_add_f32_e32 v102, v102, v104
	s_waitcnt lgkmcnt(0)
	v_add_f32_e32 v104, v105, v106
	ds_bpermute_b32 v101, v138, v99
	ds_bpermute_b32 v103, v138, v102
	ds_bpermute_b32 v105, v138, v104
	v_add_u32_e32 v96, 32, v132
	v_ashrrev_i32_e32 v97, 31, v96
	s_and_saveexec_b64 s[6:7], vcc
	s_cbranch_execz .LBB0_187
	s_waitcnt lgkmcnt(2)
	v_add_f32_e32 v101, v99, v101
	v_add_f32_e32 v100, v100, v98
	v_lshl_add_u64 v[98:99], v[96:97], 2, s[16:17]
	s_waitcnt lgkmcnt(0)
	v_add_f32_e32 v104, v104, v105
	v_add_f32_e32 v102, v102, v103
	global_atomic_add_f32 v[98:99], v100, off
	global_atomic_add_f32 v[116:117], v101, off offset:132
	global_atomic_add_f32 v[116:117], v102, off offset:136
	global_atomic_add_f32 v[116:117], v104, off offset:140
.LBB0_187:
	s_or_b64 exec, exec, s[6:7]
	v_ashrrev_i32_e32 v98, 7, v96
	v_ashrrev_i32_e32 v99, 31, v98
	v_lshlrev_b64 v[98:99], 18, v[98:99]
	v_and_b32_e32 v96, 0x7f, v96
	v_lshl_add_u64 v[98:99], s[14:15], 0, v[98:99]
	v_lshlrev_b32_e32 v204, 1, v96
	v_lshl_add_u64 v[96:97], v[98:99], 0, v[204:205]
	v_cvt_pk_bf16_f32 v92, v92, v93
	v_cvt_pk_bf16_f32 v93, v94, v95
	v_lshl_add_u64 v[94:95], v[96:97], 0, v[118:119]
	v_cvt_pk_bf16_f32 v88, v88, v89
	v_cvt_pk_bf16_f32 v89, v90, v91
	v_lshl_add_u64 v[90:91], v[96:97], 0, v[120:121]
	v_cvt_pk_bf16_f32 v84, v84, v85
	v_cvt_pk_bf16_f32 v85, v86, v87
	v_lshl_add_u64 v[86:87], v[96:97], 0, v[122:123]
	v_cvt_pk_bf16_f32 v80, v80, v81
	v_cvt_pk_bf16_f32 v81, v82, v83
	v_lshl_add_u64 v[82:83], v[96:97], 0, v[124:125]
	global_store_dwordx2 v[94:95], v[92:93], off
	global_store_dwordx2 v[90:91], v[88:89], off
	global_store_dwordx2 v[86:87], v[84:85], off
	global_store_dwordx2 v[82:83], v[80:81], off
	s_nop 1
	v_mov_b64_e32 v[80:81], v[222:223]
	v_mov_b64_e32 v[82:83], v[224:225]
	v_pk_mul_f32 v[72:73], v[72:73], v[80:81]
	v_pk_mul_f32 v[68:69], v[68:69], v[80:81]
	v_mul_f32_e32 v84, 0x3d372713, v72
	v_mul_f32_e32 v85, 0x3d372713, v73
	v_mul_f32_e32 v86, 0x3d372713, v68
	v_mul_f32_e32 v87, 0x3d372713, v69
	v_mul_f32_e32 v84, v72, v84
	v_mul_f32_e32 v85, v73, v85
	v_mul_f32_e32 v86, v68, v86
	v_mul_f32_e32 v87, v69, v87
	v_fma_f32 v84, v72, v84, v72
	v_fma_f32 v85, v73, v85, v73
	v_fma_f32 v86, v68, v86, v68
	v_fma_f32 v87, v69, v87, v69
	v_mul_f32_e32 v84, 0x3f4c422a, v84
	v_mul_f32_e32 v85, 0x3f4c422a, v85
	v_mul_f32_e32 v86, 0x3f4c422a, v86
	v_mul_f32_e32 v87, 0x3f4c422a, v87
	v_mul_f32_e32 v84, 0xc038aa3b, v84
	v_mul_f32_e32 v85, 0xc038aa3b, v85
; template <int EPI>
; __device__ __forceinline__ void gemm_tile(const Params& p, const u16* __restrict__ A, int lda, const u16* __restrict__ Bt, int ldb,
;                                           int K, int brow, int bcol, bool prefetched, int nbrow, int nbcol, char* shm) {
;     ...
;       for (int j = 0; j < 4; ++j) {
;         const float r1 = rstd1[rowb + j]; float s = 0.f;
; #pragma unroll
;         for (int n = 0; n < 4; ++n) { g[n][j] = gelu_tanh(acc[m][n][j] * r1); s += g[n][j] * g[n][j]; }
;         s4[j] = red16(s);
;       }
;       if (fr == 0) {
; #pragma unroll
;         for (int j = 0; j < 4; ++j) unsafeAtomicAdd(&ssq[rowb + j], s4[j]);
	v_mul_f32_e32 v86, 0xc038aa3b, v86
	v_mul_f32_e32 v87, 0xc038aa3b, v87
	v_exp_f32_e32 v84, v84
	v_exp_f32_e32 v85, v85
	v_exp_f32_e32 v86, v86
	v_exp_f32_e32 v87, v87
	v_add_f32_e32 v84, 1.0, v84
	v_add_f32_e32 v85, 1.0, v85
	v_pk_mul_f32 v[78:79], v[78:79], v[82:83]
	v_add_f32_e32 v86, 1.0, v86
	v_add_f32_e32 v87, 1.0, v87
	v_rcp_f32_e32 v84, v84
	v_rcp_f32_e32 v85, v85
	v_pk_mul_f32 v[64:65], v[64:65], v[80:81]
	v_mul_f32_e32 v90, 0x3d372713, v78
	v_rcp_f32_e32 v86, v86
	v_rcp_f32_e32 v87, v87
	v_mul_f32_e32 v88, 0x3d372713, v64
	v_mul_f32_e32 v89, 0x3d372713, v65
	v_mul_f32_e32 v91, 0x3d372713, v79
	v_mul_f32_e32 v90, v78, v90
	v_mul_f32_e32 v88, v64, v88
	v_mul_f32_e32 v89, v65, v89
	v_mul_f32_e32 v91, v79, v91
	v_fma_f32 v90, v78, v90, v78
	v_fma_f32 v88, v64, v88, v64
	v_fma_f32 v89, v65, v89, v65
	v_fma_f32 v91, v79, v91, v79
	v_pk_mul_f32 v[72:73], v[72:73], v[84:85]
	v_mul_f32_e32 v85, 0x3f4c422a, v90
	v_mul_f32_e32 v88, 0x3f4c422a, v88
	v_mul_f32_e32 v89, 0x3f4c422a, v89
	v_pk_mul_f32 v[68:69], v[68:69], v[86:87]
	v_mul_f32_e32 v86, 0x3f4c422a, v91
	v_mul_f32_e32 v85, 0xc038aa3b, v85
	v_mul_f32_e32 v88, 0xc038aa3b, v88
	v_mul_f32_e32 v89, 0xc038aa3b, v89
	v_exp_f32_e32 v85, v85
	v_mul_f32_e32 v86, 0xc038aa3b, v86
	v_exp_f32_e32 v88, v88
	v_exp_f32_e32 v89, v89
	v_exp_f32_e32 v87, v86
	v_pk_mul_f32 v[76:77], v[76:77], v[80:81]
	v_add_f32_e32 v85, 1.0, v85
	v_mul_f32_e32 v80, 0x3d372713, v76
	v_mul_f32_e32 v81, 0x3d372713, v77
	v_mul_f32_e32 v80, v76, v80
	v_mul_f32_e32 v81, v77, v81
	v_pk_mul_f32 v[74:75], v[74:75], v[82:83]
	v_fma_f32 v80, v76, v80, v76
	v_fma_f32 v81, v77, v81, v77
	v_add_f32_e32 v88, 1.0, v88
	v_add_f32_e32 v89, 1.0, v89
	v_rcp_f32_e32 v86, v85
	v_add_f32_e32 v85, 1.0, v87
	v_mul_f32_e32 v87, 0x3d372713, v74
	v_mul_f32_e32 v80, 0x3f4c422a, v80
	v_mul_f32_e32 v81, 0x3f4c422a, v81
	v_rcp_f32_e32 v88, v88
	v_rcp_f32_e32 v89, v89
	v_mul_f32_e32 v87, v74, v87
	v_mul_f32_e32 v80, 0xc038aa3b, v80
	v_mul_f32_e32 v81, 0xc038aa3b, v81
	v_fma_f32 v87, v74, v87, v74
	v_exp_f32_e32 v80, v80
	v_exp_f32_e32 v81, v81
	v_mul_f32_e32 v87, 0x3f4c422a, v87
	v_mul_f32_e32 v87, 0xc038aa3b, v87
	v_pk_mul_f32 v[64:65], v[64:65], v[88:89]
	v_exp_f32_e32 v88, v87
	v_mul_f32_e32 v87, 0x3d372713, v75
	v_mul_f32_e32 v87, v75, v87
	v_add_f32_e32 v80, 1.0, v80
	v_add_f32_e32 v81, 1.0, v81
	v_fma_f32 v87, v75, v87, v75
	v_rcp_f32_e32 v80, v80
	v_rcp_f32_e32 v81, v81
	v_mul_f32_e32 v87, 0x3f4c422a, v87
	v_mul_f32_e32 v87, 0xc038aa3b, v87
	v_exp_f32_e32 v89, v87
	v_pk_mul_f32 v[76:77], v[76:77], v[80:81]
	v_pk_mul_f32 v[80:81], v[72:73], v[72:73]
	v_rcp_f32_e32 v87, v85
	v_pk_fma_f32 v[80:81], v[76:77], v[76:77], v[80:81]
	v_add_f32_e32 v85, 1.0, v88
	v_pk_fma_f32 v[80:81], v[68:69], v[68:69], v[80:81]
	v_rcp_f32_e32 v88, v85
	v_add_f32_e32 v85, 1.0, v89
	v_pk_mul_f32 v[70:71], v[70:71], v[82:83]
	v_pk_fma_f32 v[80:81], v[64:65], v[64:65], v[80:81]
	v_rcp_f32_e32 v89, v85
	v_mul_f32_e32 v85, 0x3d372713, v70
	ds_bpermute_b32 v84, v141, v80
	v_pk_mul_f32 v[78:79], v[78:79], v[86:87]
	v_mul_f32_e32 v85, v70, v85
	v_mul_f32_e32 v86, 0x3d372713, v71
	v_pk_mul_f32 v[66:67], v[66:67], v[82:83]
	v_fma_f32 v85, v70, v85, v70
	v_mul_f32_e32 v86, v71, v86
	v_mul_f32_e32 v82, 0x3d372713, v66
	v_mul_f32_e32 v83, 0x3d372713, v67
	v_mul_f32_e32 v85, 0x3f4c422a, v85
	v_fma_f32 v86, v71, v86, v71
	v_mul_f32_e32 v82, v66, v82
	v_mul_f32_e32 v83, v67, v83
	v_mul_f32_e32 v85, 0xc038aa3b, v85
	v_mul_f32_e32 v86, 0x3f4c422a, v86
	v_fma_f32 v82, v66, v82, v66
	v_fma_f32 v83, v67, v83, v67
	v_exp_f32_e32 v85, v85
	v_mul_f32_e32 v86, 0xc038aa3b, v86
	v_mul_f32_e32 v82, 0x3f4c422a, v82
	v_mul_f32_e32 v83, 0x3f4c422a, v83
	s_waitcnt lgkmcnt(0)
	v_add_f32_e32 v80, v80, v84
	v_pk_mul_f32 v[74:75], v[74:75], v[88:89]
	v_exp_f32_e32 v89, v86
	v_mul_f32_e32 v82, 0xc038aa3b, v82
	v_mul_f32_e32 v83, 0xc038aa3b, v83
	ds_bpermute_b32 v84, v140, v80
	v_exp_f32_e32 v82, v82
	v_exp_f32_e32 v83, v83
	v_add_f32_e32 v85, 1.0, v85
	v_rcp_f32_e32 v88, v85
	v_add_f32_e32 v85, 1.0, v89
	v_rcp_f32_e32 v89, v85
	v_add_f32_e32 v82, 1.0, v82
	v_add_f32_e32 v83, 1.0, v83
	s_waitcnt lgkmcnt(0)
	v_add_f32_e32 v80, v80, v84
	v_rcp_f32_e32 v82, v82
	v_rcp_f32_e32 v83, v83
	ds_bpermute_b32 v84, v139, v80
	v_pk_mul_f32 v[86:87], v[74:75], v[74:75]
	v_pk_mul_f32 v[70:71], v[70:71], v[88:89]
	v_pk_fma_f32 v[86:87], v[78:79], v[78:79], v[86:87]
	v_pk_mul_f32 v[66:67], v[66:67], v[82:83]
	v_pk_fma_f32 v[86:87], v[70:71], v[70:71], v[86:87]
	s_waitcnt lgkmcnt(0)
	v_add_f32_e32 v84, v80, v84
	v_pk_fma_f32 v[86:87], v[66:67], v[66:67], v[86:87]
	ds_bpermute_b32 v80, v141, v81
	ds_bpermute_b32 v83, v141, v86
	ds_bpermute_b32 v85, v141, v87
	ds_bpermute_b32 v82, v138, v84
	s_waitcnt lgkmcnt(3)
	v_add_f32_e32 v80, v81, v80
	s_waitcnt lgkmcnt(2)
	v_add_f32_e32 v83, v86, v83
	s_waitcnt lgkmcnt(1)
	v_add_f32_e32 v85, v87, v85
	ds_bpermute_b32 v81, v140, v80
	ds_bpermute_b32 v86, v140, v83
	ds_bpermute_b32 v87, v140, v85
	s_waitcnt lgkmcnt(2)
	v_add_f32_e32 v80, v80, v81
	s_waitcnt lgkmcnt(1)
	v_add_f32_e32 v86, v83, v86
	s_waitcnt lgkmcnt(0)
	v_add_f32_e32 v89, v85, v87
	ds_bpermute_b32 v81, v139, v80
	ds_bpermute_b32 v88, v139, v86
	ds_bpermute_b32 v90, v139, v89
	s_waitcnt lgkmcnt(2)
	v_add_f32_e32 v83, v80, v81
	s_waitcnt lgkmcnt(1)
	v_add_f32_e32 v86, v86, v88
	s_waitcnt lgkmcnt(0)
	v_add_f32_e32 v88, v89, v90
	ds_bpermute_b32 v85, v138, v83
	ds_bpermute_b32 v87, v138, v86
	ds_bpermute_b32 v89, v138, v88
	v_add_u32_e32 v80, 48, v132
	v_ashrrev_i32_e32 v81, 31, v80
	s_and_saveexec_b64 s[6:7], vcc
	s_cbranch_execz .LBB0_189
	s_waitcnt lgkmcnt(2)
	v_add_f32_e32 v85, v83, v85
	v_add_f32_e32 v84, v84, v82
	v_lshl_add_u64 v[82:83], v[80:81], 2, s[16:17]
	s_waitcnt lgkmcnt(0)
	v_add_f32_e32 v88, v88, v89
	v_add_f32_e32 v86, v86, v87
	global_atomic_add_f32 v[82:83], v84, off
	global_atomic_add_f32 v[116:117], v85, off offset:196
	global_atomic_add_f32 v[116:117], v86, off offset:200
	global_atomic_add_f32 v[116:117], v88, off offset:204
; template <int EPI>
; __device__ __forceinline__ void gemm_tile(const Params& p, const u16* __restrict__ A, int lda, const u16* __restrict__ Bt, int ldb,
;                                           int K, int brow, int bcol, bool prefetched, int nbrow, int nbcol, char* shm) {
;     ...
;     for (int m = 0; m < 8; ++m) {
;       const int rowb = row0 + m * 16; float g[4][4], s4[4];
; #pragma unroll
;       for (int j = 0; j < 4; ++j) {
;         const float r1 = rstd1[rowb + j]; float s = 0.f;
; #pragma unroll
;         for (int n = 0; n < 4; ++n) { g[n][j] = gelu_tanh(acc[m][n][j] * r1); s += g[n][j] * g[n][j]; }
;     ...
; #pragma unroll
;       for (int n = 0; n < 4; ++n) {
;         u32x2 w = {cvtpk(g[n][0], g[n][1]), cvtpk(g[n][2], g[n][3])};
;         *(u32x2*)(dst + (long)(rowb >> 7) * 131072 + (long)(cb + n * 16 + fr) * 128 + (rowb & 127)) = w;
;       }
.LBB0_189:
	s_or_b64 exec, exec, s[6:7]
	v_ashrrev_i32_e32 v82, 7, v80
	v_ashrrev_i32_e32 v83, 31, v82
	v_lshlrev_b64 v[82:83], 18, v[82:83]
	v_and_b32_e32 v80, 0x7f, v80
	v_lshl_add_u64 v[82:83], s[14:15], 0, v[82:83]
	v_lshlrev_b32_e32 v204, 1, v80
	v_lshl_add_u64 v[80:81], v[82:83], 0, v[204:205]
	v_cvt_pk_bf16_f32 v76, v76, v77
	v_cvt_pk_bf16_f32 v77, v78, v79
	v_lshl_add_u64 v[78:79], v[80:81], 0, v[118:119]
	v_cvt_pk_bf16_f32 v72, v72, v73
	v_cvt_pk_bf16_f32 v73, v74, v75
	v_lshl_add_u64 v[74:75], v[80:81], 0, v[120:121]
	v_cvt_pk_bf16_f32 v68, v68, v69
	v_cvt_pk_bf16_f32 v69, v70, v71
	v_lshl_add_u64 v[70:71], v[80:81], 0, v[122:123]
	v_cvt_pk_bf16_f32 v64, v64, v65
	v_cvt_pk_bf16_f32 v65, v66, v67
	v_lshl_add_u64 v[66:67], v[80:81], 0, v[124:125]
	global_store_dwordx2 v[78:79], v[76:77], off
	global_store_dwordx2 v[74:75], v[72:73], off
	global_store_dwordx2 v[70:71], v[68:69], off
	global_store_dwordx2 v[66:67], v[64:65], off
	s_nop 1
	v_mov_b64_e32 v[64:65], v[226:227]
	v_mov_b64_e32 v[66:67], v[228:229]
	v_pk_mul_f32 v[56:57], v[56:57], v[64:65]
	v_pk_mul_f32 v[52:53], v[52:53], v[64:65]
	v_mul_f32_e32 v68, 0x3d372713, v56
	v_mul_f32_e32 v69, 0x3d372713, v57
	v_mul_f32_e32 v70, 0x3d372713, v52
	v_mul_f32_e32 v71, 0x3d372713, v53
	v_mul_f32_e32 v68, v56, v68
	v_mul_f32_e32 v69, v57, v69
	v_mul_f32_e32 v70, v52, v70
	v_mul_f32_e32 v71, v53, v71
	v_fma_f32 v68, v56, v68, v56
	v_fma_f32 v69, v57, v69, v57
	v_fma_f32 v70, v52, v70, v52
	v_fma_f32 v71, v53, v71, v53
	v_mul_f32_e32 v68, 0x3f4c422a, v68
	v_mul_f32_e32 v69, 0x3f4c422a, v69
	v_mul_f32_e32 v70, 0x3f4c422a, v70
	v_mul_f32_e32 v71, 0x3f4c422a, v71
	v_mul_f32_e32 v68, 0xc038aa3b, v68
	v_mul_f32_e32 v69, 0xc038aa3b, v69
	v_mul_f32_e32 v70, 0xc038aa3b, v70
	v_mul_f32_e32 v71, 0xc038aa3b, v71
	v_exp_f32_e32 v68, v68
	v_exp_f32_e32 v69, v69
	v_exp_f32_e32 v70, v70
	v_exp_f32_e32 v71, v71
	v_add_f32_e32 v68, 1.0, v68
	v_add_f32_e32 v69, 1.0, v69
	v_pk_mul_f32 v[62:63], v[62:63], v[66:67]
	v_add_f32_e32 v70, 1.0, v70
	v_add_f32_e32 v71, 1.0, v71
	v_rcp_f32_e32 v68, v68
	v_rcp_f32_e32 v69, v69
	v_pk_mul_f32 v[48:49], v[48:49], v[64:65]
	v_mul_f32_e32 v74, 0x3d372713, v62
	v_rcp_f32_e32 v70, v70
	v_rcp_f32_e32 v71, v71
	v_mul_f32_e32 v72, 0x3d372713, v48
	v_mul_f32_e32 v73, 0x3d372713, v49
	v_mul_f32_e32 v75, 0x3d372713, v63
	v_mul_f32_e32 v74, v62, v74
	v_mul_f32_e32 v72, v48, v72
	v_mul_f32_e32 v73, v49, v73
	v_mul_f32_e32 v75, v63, v75
	v_fma_f32 v74, v62, v74, v62
	v_fma_f32 v72, v48, v72, v48
	v_fma_f32 v73, v49, v73, v49
	v_fma_f32 v75, v63, v75, v63
	v_pk_mul_f32 v[56:57], v[56:57], v[68:69]
	v_mul_f32_e32 v69, 0x3f4c422a, v74
	v_mul_f32_e32 v72, 0x3f4c422a, v72
	v_mul_f32_e32 v73, 0x3f4c422a, v73
	v_pk_mul_f32 v[52:53], v[52:53], v[70:71]
	v_mul_f32_e32 v70, 0x3f4c422a, v75
	v_mul_f32_e32 v69, 0xc038aa3b, v69
	v_mul_f32_e32 v72, 0xc038aa3b, v72
	v_mul_f32_e32 v73, 0xc038aa3b, v73
	v_exp_f32_e32 v69, v69
	v_mul_f32_e32 v70, 0xc038aa3b, v70
	v_exp_f32_e32 v72, v72
	v_exp_f32_e32 v73, v73
	v_exp_f32_e32 v71, v70
	v_pk_mul_f32 v[60:61], v[60:61], v[64:65]
	v_add_f32_e32 v69, 1.0, v69
	v_mul_f32_e32 v64, 0x3d372713, v60
	v_mul_f32_e32 v65, 0x3d372713, v61
	v_mul_f32_e32 v64, v60, v64
	v_mul_f32_e32 v65, v61, v65
	v_pk_mul_f32 v[58:59], v[58:59], v[66:67]
	v_fma_f32 v64, v60, v64, v60
	v_fma_f32 v65, v61, v65, v61
	v_add_f32_e32 v72, 1.0, v72
	v_add_f32_e32 v73, 1.0, v73
	v_rcp_f32_e32 v70, v69
	v_add_f32_e32 v69, 1.0, v71
	v_mul_f32_e32 v71, 0x3d372713, v58
	v_mul_f32_e32 v64, 0x3f4c422a, v64
	v_mul_f32_e32 v65, 0x3f4c422a, v65
	v_rcp_f32_e32 v72, v72
	v_rcp_f32_e32 v73, v73
	v_mul_f32_e32 v71, v58, v71
	v_mul_f32_e32 v64, 0xc038aa3b, v64
	v_mul_f32_e32 v65, 0xc038aa3b, v65
	v_fma_f32 v71, v58, v71, v58
	v_exp_f32_e32 v64, v64
	v_exp_f32_e32 v65, v65
	v_mul_f32_e32 v71, 0x3f4c422a, v71
	v_mul_f32_e32 v71, 0xc038aa3b, v71
	v_pk_mul_f32 v[48:49], v[48:49], v[72:73]
	v_exp_f32_e32 v72, v71
	v_mul_f32_e32 v71, 0x3d372713, v59
	v_mul_f32_e32 v71, v59, v71
	v_add_f32_e32 v64, 1.0, v64
	v_add_f32_e32 v65, 1.0, v65
	v_fma_f32 v71, v59, v71, v59
	v_rcp_f32_e32 v64, v64
	v_rcp_f32_e32 v65, v65
	v_mul_f32_e32 v71, 0x3f4c422a, v71
	v_mul_f32_e32 v71, 0xc038aa3b, v71
	v_exp_f32_e32 v73, v71
	v_pk_mul_f32 v[60:61], v[60:61], v[64:65]
	v_pk_mul_f32 v[64:65], v[56:57], v[56:57]
	v_rcp_f32_e32 v71, v69
	v_pk_fma_f32 v[64:65], v[60:61], v[60:61], v[64:65]
	v_add_f32_e32 v69, 1.0, v72
	v_pk_fma_f32 v[64:65], v[52:53], v[52:53], v[64:65]
	v_rcp_f32_e32 v72, v69
	v_add_f32_e32 v69, 1.0, v73
	v_pk_mul_f32 v[54:55], v[54:55], v[66:67]
	v_pk_fma_f32 v[64:65], v[48:49], v[48:49], v[64:65]
	v_rcp_f32_e32 v73, v69
	v_mul_f32_e32 v69, 0x3d372713, v54
	ds_bpermute_b32 v68, v141, v64
	v_pk_mul_f32 v[62:63], v[62:63], v[70:71]
	v_mul_f32_e32 v69, v54, v69
	v_mul_f32_e32 v70, 0x3d372713, v55
	v_pk_mul_f32 v[50:51], v[50:51], v[66:67]
	v_fma_f32 v69, v54, v69, v54
	v_mul_f32_e32 v70, v55, v70
	v_mul_f32_e32 v66, 0x3d372713, v50
	v_mul_f32_e32 v67, 0x3d372713, v51
	v_mul_f32_e32 v69, 0x3f4c422a, v69
	v_fma_f32 v70, v55, v70, v55
	v_mul_f32_e32 v66, v50, v66
	v_mul_f32_e32 v67, v51, v67
	v_mul_f32_e32 v69, 0xc038aa3b, v69
	v_mul_f32_e32 v70, 0x3f4c422a, v70
	v_fma_f32 v66, v50, v66, v50
	v_fma_f32 v67, v51, v67, v51
	v_exp_f32_e32 v69, v69
	v_mul_f32_e32 v70, 0xc038aa3b, v70
	v_mul_f32_e32 v66, 0x3f4c422a, v66
	v_mul_f32_e32 v67, 0x3f4c422a, v67
	s_waitcnt lgkmcnt(0)
	v_add_f32_e32 v64, v64, v68
	v_pk_mul_f32 v[58:59], v[58:59], v[72:73]
	v_exp_f32_e32 v73, v70
	v_mul_f32_e32 v66, 0xc038aa3b, v66
	v_mul_f32_e32 v67, 0xc038aa3b, v67
	ds_bpermute_b32 v68, v140, v64
	v_exp_f32_e32 v66, v66
	v_exp_f32_e32 v67, v67
	v_add_f32_e32 v69, 1.0, v69
	v_rcp_f32_e32 v72, v69
	v_add_f32_e32 v69, 1.0, v73
	v_rcp_f32_e32 v73, v69
	v_add_f32_e32 v66, 1.0, v66
	v_add_f32_e32 v67, 1.0, v67
	s_waitcnt lgkmcnt(0)
; template <int EPI>
; __device__ __forceinline__ void gemm_tile(const Params& p, const u16* __restrict__ A, int lda, const u16* __restrict__ Bt, int ldb,
;                                           int K, int brow, int bcol, bool prefetched, int nbrow, int nbcol, char* shm) {
;     ...
;       for (int j = 0; j < 4; ++j) {
;         const float r1 = rstd1[rowb + j]; float s = 0.f;
; #pragma unroll
;         for (int n = 0; n < 4; ++n) { g[n][j] = gelu_tanh(acc[m][n][j] * r1); s += g[n][j] * g[n][j]; }
;         s4[j] = red16(s);
;       }
;       if (fr == 0) {
; #pragma unroll
;         for (int j = 0; j < 4; ++j) unsafeAtomicAdd(&ssq[rowb + j], s4[j]);
;       }
; #pragma unroll
;       for (int n = 0; n < 4; ++n) {
;         u32x2 w = {cvtpk(g[n][0], g[n][1]), cvtpk(g[n][2], g[n][3])};
;         *(u32x2*)(dst + (long)(rowb >> 7) * 131072 + (long)(cb + n * 16 + fr) * 128 + (rowb & 127)) = w;
;       }
	v_add_f32_e32 v64, v64, v68
	v_rcp_f32_e32 v66, v66
	v_rcp_f32_e32 v67, v67
	ds_bpermute_b32 v68, v139, v64
	v_pk_mul_f32 v[70:71], v[58:59], v[58:59]
	v_pk_mul_f32 v[54:55], v[54:55], v[72:73]
	v_pk_fma_f32 v[70:71], v[62:63], v[62:63], v[70:71]
	v_pk_mul_f32 v[50:51], v[50:51], v[66:67]
	v_pk_fma_f32 v[70:71], v[54:55], v[54:55], v[70:71]
	s_waitcnt lgkmcnt(0)
	v_add_f32_e32 v68, v64, v68
	v_pk_fma_f32 v[70:71], v[50:51], v[50:51], v[70:71]
	ds_bpermute_b32 v64, v141, v65
	ds_bpermute_b32 v67, v141, v70
	ds_bpermute_b32 v69, v141, v71
	ds_bpermute_b32 v66, v138, v68
	s_waitcnt lgkmcnt(3)
	v_add_f32_e32 v64, v65, v64
	s_waitcnt lgkmcnt(2)
	v_add_f32_e32 v67, v70, v67
	s_waitcnt lgkmcnt(1)
	v_add_f32_e32 v69, v71, v69
	ds_bpermute_b32 v65, v140, v64
	ds_bpermute_b32 v70, v140, v67
	ds_bpermute_b32 v71, v140, v69
	s_waitcnt lgkmcnt(2)
	v_add_f32_e32 v64, v64, v65
	s_waitcnt lgkmcnt(1)
	v_add_f32_e32 v70, v67, v70
	s_waitcnt lgkmcnt(0)
	v_add_f32_e32 v73, v69, v71
	ds_bpermute_b32 v65, v139, v64
	ds_bpermute_b32 v72, v139, v70
	ds_bpermute_b32 v74, v139, v73
	s_waitcnt lgkmcnt(2)
	v_add_f32_e32 v67, v64, v65
	s_waitcnt lgkmcnt(1)
	v_add_f32_e32 v70, v70, v72
	s_waitcnt lgkmcnt(0)
	v_add_f32_e32 v72, v73, v74
	ds_bpermute_b32 v69, v138, v67
	ds_bpermute_b32 v71, v138, v70
	ds_bpermute_b32 v73, v138, v72
	v_add_u32_e32 v64, 64, v132
	v_ashrrev_i32_e32 v65, 31, v64
	s_and_saveexec_b64 s[6:7], vcc
	s_cbranch_execz .LBB0_191
	s_waitcnt lgkmcnt(2)
	v_add_f32_e32 v69, v67, v69
	v_add_f32_e32 v68, v68, v66
	v_lshl_add_u64 v[66:67], v[64:65], 2, s[16:17]
	s_waitcnt lgkmcnt(0)
	v_add_f32_e32 v72, v72, v73
	v_add_f32_e32 v70, v70, v71
	global_atomic_add_f32 v[66:67], v68, off
	global_atomic_add_f32 v[116:117], v69, off offset:260
	global_atomic_add_f32 v[116:117], v70, off offset:264
	global_atomic_add_f32 v[116:117], v72, off offset:268
.LBB0_191:
	s_or_b64 exec, exec, s[6:7]
	v_ashrrev_i32_e32 v66, 7, v64
	v_ashrrev_i32_e32 v67, 31, v66
	v_lshlrev_b64 v[66:67], 18, v[66:67]
	v_and_b32_e32 v64, 0x7f, v64
	v_lshl_add_u64 v[66:67], s[14:15], 0, v[66:67]
	v_lshlrev_b32_e32 v204, 1, v64
	v_lshl_add_u64 v[64:65], v[66:67], 0, v[204:205]
	v_cvt_pk_bf16_f32 v60, v60, v61
	v_cvt_pk_bf16_f32 v61, v62, v63
	v_lshl_add_u64 v[62:63], v[64:65], 0, v[118:119]
	v_cvt_pk_bf16_f32 v56, v56, v57
	v_cvt_pk_bf16_f32 v57, v58, v59
	v_lshl_add_u64 v[58:59], v[64:65], 0, v[120:121]
	v_cvt_pk_bf16_f32 v52, v52, v53
	v_cvt_pk_bf16_f32 v53, v54, v55
	v_lshl_add_u64 v[54:55], v[64:65], 0, v[122:123]
	v_cvt_pk_bf16_f32 v48, v48, v49
	v_cvt_pk_bf16_f32 v49, v50, v51
	v_lshl_add_u64 v[50:51], v[64:65], 0, v[124:125]
	global_store_dwordx2 v[62:63], v[60:61], off
	global_store_dwordx2 v[58:59], v[56:57], off
	global_store_dwordx2 v[54:55], v[52:53], off
	global_store_dwordx2 v[50:51], v[48:49], off
	s_nop 1
	v_mov_b64_e32 v[48:49], v[230:231]
	v_mov_b64_e32 v[50:51], v[232:233]
	v_pk_mul_f32 v[40:41], v[40:41], v[48:49]
	v_pk_mul_f32 v[36:37], v[36:37], v[48:49]
	v_mul_f32_e32 v52, 0x3d372713, v40
	v_mul_f32_e32 v53, 0x3d372713, v41
	v_mul_f32_e32 v54, 0x3d372713, v36
	v_mul_f32_e32 v55, 0x3d372713, v37
	v_mul_f32_e32 v52, v40, v52
	v_mul_f32_e32 v53, v41, v53
	v_mul_f32_e32 v54, v36, v54
	v_mul_f32_e32 v55, v37, v55
	v_fma_f32 v52, v40, v52, v40
	v_fma_f32 v53, v41, v53, v41
	v_fma_f32 v54, v36, v54, v36
	v_fma_f32 v55, v37, v55, v37
	v_mul_f32_e32 v52, 0x3f4c422a, v52
	v_mul_f32_e32 v53, 0x3f4c422a, v53
	v_mul_f32_e32 v54, 0x3f4c422a, v54
	v_mul_f32_e32 v55, 0x3f4c422a, v55
	v_mul_f32_e32 v52, 0xc038aa3b, v52
	v_mul_f32_e32 v53, 0xc038aa3b, v53
	v_mul_f32_e32 v54, 0xc038aa3b, v54
	v_mul_f32_e32 v55, 0xc038aa3b, v55
	v_exp_f32_e32 v52, v52
	v_exp_f32_e32 v53, v53
	v_exp_f32_e32 v54, v54
	v_exp_f32_e32 v55, v55
	v_add_f32_e32 v52, 1.0, v52
	v_add_f32_e32 v53, 1.0, v53
	v_pk_mul_f32 v[46:47], v[46:47], v[50:51]
	v_add_f32_e32 v54, 1.0, v54
	v_add_f32_e32 v55, 1.0, v55
	v_rcp_f32_e32 v52, v52
	v_rcp_f32_e32 v53, v53
	v_pk_mul_f32 v[32:33], v[32:33], v[48:49]
	v_mul_f32_e32 v58, 0x3d372713, v46
	v_rcp_f32_e32 v54, v54
	v_rcp_f32_e32 v55, v55
	v_mul_f32_e32 v56, 0x3d372713, v32
	v_mul_f32_e32 v57, 0x3d372713, v33
	v_mul_f32_e32 v59, 0x3d372713, v47
	v_mul_f32_e32 v58, v46, v58
	v_mul_f32_e32 v56, v32, v56
	v_mul_f32_e32 v57, v33, v57
	v_mul_f32_e32 v59, v47, v59
	v_fma_f32 v58, v46, v58, v46
	v_fma_f32 v56, v32, v56, v32
	v_fma_f32 v57, v33, v57, v33
	v_fma_f32 v59, v47, v59, v47
	v_pk_mul_f32 v[40:41], v[40:41], v[52:53]
	v_mul_f32_e32 v53, 0x3f4c422a, v58
	v_mul_f32_e32 v56, 0x3f4c422a, v56
	v_mul_f32_e32 v57, 0x3f4c422a, v57
	v_pk_mul_f32 v[36:37], v[36:37], v[54:55]
	v_mul_f32_e32 v54, 0x3f4c422a, v59
	v_mul_f32_e32 v53, 0xc038aa3b, v53
	v_mul_f32_e32 v56, 0xc038aa3b, v56
	v_mul_f32_e32 v57, 0xc038aa3b, v57
	v_exp_f32_e32 v53, v53
	v_mul_f32_e32 v54, 0xc038aa3b, v54
	v_exp_f32_e32 v56, v56
	v_exp_f32_e32 v57, v57
	v_exp_f32_e32 v55, v54
	v_pk_mul_f32 v[44:45], v[44:45], v[48:49]
	v_add_f32_e32 v53, 1.0, v53
	v_mul_f32_e32 v48, 0x3d372713, v44
	v_mul_f32_e32 v49, 0x3d372713, v45
	v_mul_f32_e32 v48, v44, v48
	v_mul_f32_e32 v49, v45, v49
	v_pk_mul_f32 v[42:43], v[42:43], v[50:51]
	v_fma_f32 v48, v44, v48, v44
	v_fma_f32 v49, v45, v49, v45
	v_add_f32_e32 v56, 1.0, v56
	v_add_f32_e32 v57, 1.0, v57
	v_rcp_f32_e32 v54, v53
	v_add_f32_e32 v53, 1.0, v55
	v_mul_f32_e32 v55, 0x3d372713, v42
	v_mul_f32_e32 v48, 0x3f4c422a, v48
	v_mul_f32_e32 v49, 0x3f4c422a, v49
	v_rcp_f32_e32 v56, v56
	v_rcp_f32_e32 v57, v57
	v_mul_f32_e32 v55, v42, v55
	v_mul_f32_e32 v48, 0xc038aa3b, v48
	v_mul_f32_e32 v49, 0xc038aa3b, v49
	v_fma_f32 v55, v42, v55, v42
	v_exp_f32_e32 v48, v48
	v_exp_f32_e32 v49, v49
; template <int EPI>
; __device__ __forceinline__ void gemm_tile(const Params& p, const u16* __restrict__ A, int lda, const u16* __restrict__ Bt, int ldb,
;                                           int K, int brow, int bcol, bool prefetched, int nbrow, int nbcol, char* shm) {
;     ...
;       for (int j = 0; j < 4; ++j) {
;         const float r1 = rstd1[rowb + j]; float s = 0.f;
; #pragma unroll
;         for (int n = 0; n < 4; ++n) { g[n][j] = gelu_tanh(acc[m][n][j] * r1); s += g[n][j] * g[n][j]; }
;         s4[j] = red16(s);
;       }
;       if (fr == 0) {
; #pragma unroll
;         for (int j = 0; j < 4; ++j) unsafeAtomicAdd(&ssq[rowb + j], s4[j]);
;       }
; #pragma unroll
;       for (int n = 0; n < 4; ++n) {
;         u32x2 w = {cvtpk(g[n][0], g[n][1]), cvtpk(g[n][2], g[n][3])};
;         *(u32x2*)(dst + (long)(rowb >> 7) * 131072 + (long)(cb + n * 16 + fr) * 128 + (rowb & 127)) = w;
;       }
	v_mul_f32_e32 v55, 0x3f4c422a, v55
	v_mul_f32_e32 v55, 0xc038aa3b, v55
	v_pk_mul_f32 v[32:33], v[32:33], v[56:57]
	v_exp_f32_e32 v56, v55
	v_mul_f32_e32 v55, 0x3d372713, v43
	v_mul_f32_e32 v55, v43, v55
	v_add_f32_e32 v48, 1.0, v48
	v_add_f32_e32 v49, 1.0, v49
	v_fma_f32 v55, v43, v55, v43
	v_rcp_f32_e32 v48, v48
	v_rcp_f32_e32 v49, v49
	v_mul_f32_e32 v55, 0x3f4c422a, v55
	v_mul_f32_e32 v55, 0xc038aa3b, v55
	v_exp_f32_e32 v57, v55
	v_pk_mul_f32 v[44:45], v[44:45], v[48:49]
	v_pk_mul_f32 v[48:49], v[40:41], v[40:41]
	v_rcp_f32_e32 v55, v53
	v_pk_fma_f32 v[48:49], v[44:45], v[44:45], v[48:49]
	v_add_f32_e32 v53, 1.0, v56
	v_pk_fma_f32 v[48:49], v[36:37], v[36:37], v[48:49]
	v_rcp_f32_e32 v56, v53
	v_add_f32_e32 v53, 1.0, v57
	v_pk_mul_f32 v[38:39], v[38:39], v[50:51]
	v_pk_fma_f32 v[48:49], v[32:33], v[32:33], v[48:49]
	v_rcp_f32_e32 v57, v53
	v_mul_f32_e32 v53, 0x3d372713, v38
	ds_bpermute_b32 v52, v141, v48
	v_pk_mul_f32 v[46:47], v[46:47], v[54:55]
	v_mul_f32_e32 v53, v38, v53
	v_mul_f32_e32 v54, 0x3d372713, v39
	v_pk_mul_f32 v[34:35], v[34:35], v[50:51]
	v_fma_f32 v53, v38, v53, v38
	v_mul_f32_e32 v54, v39, v54
	v_mul_f32_e32 v50, 0x3d372713, v34
	v_mul_f32_e32 v51, 0x3d372713, v35
	v_mul_f32_e32 v53, 0x3f4c422a, v53
	v_fma_f32 v54, v39, v54, v39
	v_mul_f32_e32 v50, v34, v50
	v_mul_f32_e32 v51, v35, v51
	v_mul_f32_e32 v53, 0xc038aa3b, v53
	v_mul_f32_e32 v54, 0x3f4c422a, v54
	v_fma_f32 v50, v34, v50, v34
	v_fma_f32 v51, v35, v51, v35
	v_exp_f32_e32 v53, v53
	v_mul_f32_e32 v54, 0xc038aa3b, v54
	v_mul_f32_e32 v50, 0x3f4c422a, v50
	v_mul_f32_e32 v51, 0x3f4c422a, v51
	s_waitcnt lgkmcnt(0)
	v_add_f32_e32 v48, v48, v52
	v_pk_mul_f32 v[42:43], v[42:43], v[56:57]
	v_exp_f32_e32 v57, v54
	v_mul_f32_e32 v50, 0xc038aa3b, v50
	v_mul_f32_e32 v51, 0xc038aa3b, v51
	ds_bpermute_b32 v52, v140, v48
	v_exp_f32_e32 v50, v50
	v_exp_f32_e32 v51, v51
	v_add_f32_e32 v53, 1.0, v53
	v_rcp_f32_e32 v56, v53
	v_add_f32_e32 v53, 1.0, v57
	v_rcp_f32_e32 v57, v53
	v_add_f32_e32 v50, 1.0, v50
	v_add_f32_e32 v51, 1.0, v51
	s_waitcnt lgkmcnt(0)
	v_add_f32_e32 v48, v48, v52
	v_rcp_f32_e32 v50, v50
	v_rcp_f32_e32 v51, v51
	ds_bpermute_b32 v52, v139, v48
	v_pk_mul_f32 v[54:55], v[42:43], v[42:43]
	v_pk_mul_f32 v[38:39], v[38:39], v[56:57]
	v_pk_fma_f32 v[54:55], v[46:47], v[46:47], v[54:55]
	v_pk_mul_f32 v[34:35], v[34:35], v[50:51]
	v_pk_fma_f32 v[54:55], v[38:39], v[38:39], v[54:55]
	s_waitcnt lgkmcnt(0)
	v_add_f32_e32 v52, v48, v52
	v_pk_fma_f32 v[54:55], v[34:35], v[34:35], v[54:55]
	ds_bpermute_b32 v48, v141, v49
	ds_bpermute_b32 v51, v141, v54
	ds_bpermute_b32 v53, v141, v55
	ds_bpermute_b32 v50, v138, v52
	s_waitcnt lgkmcnt(3)
	v_add_f32_e32 v48, v49, v48
	s_waitcnt lgkmcnt(2)
	v_add_f32_e32 v51, v54, v51
	s_waitcnt lgkmcnt(1)
	v_add_f32_e32 v53, v55, v53
	ds_bpermute_b32 v49, v140, v48
	ds_bpermute_b32 v54, v140, v51
	ds_bpermute_b32 v55, v140, v53
	s_waitcnt lgkmcnt(2)
	v_add_f32_e32 v48, v48, v49
	s_waitcnt lgkmcnt(1)
	v_add_f32_e32 v54, v51, v54
	s_waitcnt lgkmcnt(0)
	v_add_f32_e32 v57, v53, v55
	ds_bpermute_b32 v49, v139, v48
	ds_bpermute_b32 v56, v139, v54
	ds_bpermute_b32 v58, v139, v57
	s_waitcnt lgkmcnt(2)
	v_add_f32_e32 v51, v48, v49
	s_waitcnt lgkmcnt(1)
	v_add_f32_e32 v54, v54, v56
	s_waitcnt lgkmcnt(0)
	v_add_f32_e32 v56, v57, v58
	ds_bpermute_b32 v53, v138, v51
	ds_bpermute_b32 v55, v138, v54
	ds_bpermute_b32 v57, v138, v56
	v_add_u32_e32 v48, 0x50, v132
	v_ashrrev_i32_e32 v49, 31, v48
	s_and_saveexec_b64 s[6:7], vcc
	s_cbranch_execz .LBB0_193
	s_waitcnt lgkmcnt(2)
	v_add_f32_e32 v53, v51, v53
	v_add_f32_e32 v52, v52, v50
	v_lshl_add_u64 v[50:51], v[48:49], 2, s[16:17]
	s_waitcnt lgkmcnt(0)
	v_add_f32_e32 v56, v56, v57
	v_add_f32_e32 v54, v54, v55
	global_atomic_add_f32 v[50:51], v52, off
	global_atomic_add_f32 v[116:117], v53, off offset:324
	global_atomic_add_f32 v[116:117], v54, off offset:328
	global_atomic_add_f32 v[116:117], v56, off offset:332
.LBB0_193:
	s_or_b64 exec, exec, s[6:7]
	v_ashrrev_i32_e32 v50, 7, v48
	v_ashrrev_i32_e32 v51, 31, v50
	v_lshlrev_b64 v[50:51], 18, v[50:51]
	v_and_b32_e32 v48, 0x7f, v48
	v_lshl_add_u64 v[50:51], s[14:15], 0, v[50:51]
	v_lshlrev_b32_e32 v204, 1, v48
	v_lshl_add_u64 v[48:49], v[50:51], 0, v[204:205]
	v_cvt_pk_bf16_f32 v44, v44, v45
	v_cvt_pk_bf16_f32 v45, v46, v47
	v_lshl_add_u64 v[46:47], v[48:49], 0, v[118:119]
	v_cvt_pk_bf16_f32 v40, v40, v41
	v_cvt_pk_bf16_f32 v41, v42, v43
	v_lshl_add_u64 v[42:43], v[48:49], 0, v[120:121]
	v_cvt_pk_bf16_f32 v36, v36, v37
	v_cvt_pk_bf16_f32 v37, v38, v39
	v_lshl_add_u64 v[38:39], v[48:49], 0, v[122:123]
	v_cvt_pk_bf16_f32 v32, v32, v33
	v_cvt_pk_bf16_f32 v33, v34, v35
	v_lshl_add_u64 v[34:35], v[48:49], 0, v[124:125]
	global_store_dwordx2 v[46:47], v[44:45], off
	global_store_dwordx2 v[42:43], v[40:41], off
	global_store_dwordx2 v[38:39], v[36:37], off
	global_store_dwordx2 v[34:35], v[32:33], off
	s_nop 1
	v_mov_b64_e32 v[32:33], v[234:235]
	v_mov_b64_e32 v[34:35], v[236:237]
	v_pk_mul_f32 v[24:25], v[24:25], v[32:33]
	v_pk_mul_f32 v[20:21], v[20:21], v[32:33]
	v_mul_f32_e32 v36, 0x3d372713, v24
	v_mul_f32_e32 v37, 0x3d372713, v25
	v_mul_f32_e32 v38, 0x3d372713, v20
	v_mul_f32_e32 v39, 0x3d372713, v21
	v_mul_f32_e32 v36, v24, v36
	v_mul_f32_e32 v37, v25, v37
	v_mul_f32_e32 v38, v20, v38
	v_mul_f32_e32 v39, v21, v39
	v_fma_f32 v36, v24, v36, v24
	v_fma_f32 v37, v25, v37, v25
	v_fma_f32 v38, v20, v38, v20
	v_fma_f32 v39, v21, v39, v21
	v_mul_f32_e32 v36, 0x3f4c422a, v36
	v_mul_f32_e32 v37, 0x3f4c422a, v37
	v_mul_f32_e32 v38, 0x3f4c422a, v38
	v_mul_f32_e32 v39, 0x3f4c422a, v39
	v_mul_f32_e32 v36, 0xc038aa3b, v36
	v_mul_f32_e32 v37, 0xc038aa3b, v37
	v_mul_f32_e32 v38, 0xc038aa3b, v38
; template <int EPI>
; __device__ __forceinline__ void gemm_tile(const Params& p, const u16* __restrict__ A, int lda, const u16* __restrict__ Bt, int ldb,
;                                           int K, int brow, int bcol, bool prefetched, int nbrow, int nbcol, char* shm) {
;     ...
;       for (int j = 0; j < 4; ++j) {
;         const float r1 = rstd1[rowb + j]; float s = 0.f;
; #pragma unroll
;         for (int n = 0; n < 4; ++n) { g[n][j] = gelu_tanh(acc[m][n][j] * r1); s += g[n][j] * g[n][j]; }
;         s4[j] = red16(s);
;       }
;       if (fr == 0) {
; #pragma unroll
;         for (int j = 0; j < 4; ++j) unsafeAtomicAdd(&ssq[rowb + j], s4[j]);
	v_mul_f32_e32 v39, 0xc038aa3b, v39
	v_exp_f32_e32 v36, v36
	v_exp_f32_e32 v37, v37
	v_exp_f32_e32 v38, v38
	v_exp_f32_e32 v39, v39
	v_add_f32_e32 v36, 1.0, v36
	v_add_f32_e32 v37, 1.0, v37
	v_pk_mul_f32 v[30:31], v[30:31], v[34:35]
	v_add_f32_e32 v38, 1.0, v38
	v_add_f32_e32 v39, 1.0, v39
	v_rcp_f32_e32 v36, v36
	v_rcp_f32_e32 v37, v37
	v_pk_mul_f32 v[16:17], v[16:17], v[32:33]
	v_mul_f32_e32 v42, 0x3d372713, v30
	v_rcp_f32_e32 v38, v38
	v_rcp_f32_e32 v39, v39
	v_mul_f32_e32 v40, 0x3d372713, v16
	v_mul_f32_e32 v41, 0x3d372713, v17
	v_mul_f32_e32 v43, 0x3d372713, v31
	v_mul_f32_e32 v42, v30, v42
	v_mul_f32_e32 v40, v16, v40
	v_mul_f32_e32 v41, v17, v41
	v_mul_f32_e32 v43, v31, v43
	v_fma_f32 v42, v30, v42, v30
	v_fma_f32 v40, v16, v40, v16
	v_fma_f32 v41, v17, v41, v17
	v_fma_f32 v43, v31, v43, v31
	v_pk_mul_f32 v[24:25], v[24:25], v[36:37]
	v_mul_f32_e32 v37, 0x3f4c422a, v42
	v_mul_f32_e32 v40, 0x3f4c422a, v40
	v_mul_f32_e32 v41, 0x3f4c422a, v41
	v_pk_mul_f32 v[20:21], v[20:21], v[38:39]
	v_mul_f32_e32 v38, 0x3f4c422a, v43
	v_mul_f32_e32 v37, 0xc038aa3b, v37
	v_mul_f32_e32 v40, 0xc038aa3b, v40
	v_mul_f32_e32 v41, 0xc038aa3b, v41
	v_exp_f32_e32 v37, v37
	v_mul_f32_e32 v38, 0xc038aa3b, v38
	v_exp_f32_e32 v40, v40
	v_exp_f32_e32 v41, v41
	v_exp_f32_e32 v39, v38
	v_pk_mul_f32 v[28:29], v[28:29], v[32:33]
	v_add_f32_e32 v37, 1.0, v37
	v_mul_f32_e32 v32, 0x3d372713, v28
	v_mul_f32_e32 v33, 0x3d372713, v29
	v_mul_f32_e32 v32, v28, v32
	v_mul_f32_e32 v33, v29, v33
	v_pk_mul_f32 v[26:27], v[26:27], v[34:35]
	v_fma_f32 v32, v28, v32, v28
	v_fma_f32 v33, v29, v33, v29
	v_add_f32_e32 v40, 1.0, v40
	v_add_f32_e32 v41, 1.0, v41
	v_rcp_f32_e32 v38, v37
	v_add_f32_e32 v37, 1.0, v39
	v_mul_f32_e32 v39, 0x3d372713, v26
	v_mul_f32_e32 v32, 0x3f4c422a, v32
	v_mul_f32_e32 v33, 0x3f4c422a, v33
	v_rcp_f32_e32 v40, v40
	v_rcp_f32_e32 v41, v41
	v_mul_f32_e32 v39, v26, v39
	v_mul_f32_e32 v32, 0xc038aa3b, v32
	v_mul_f32_e32 v33, 0xc038aa3b, v33
	v_fma_f32 v39, v26, v39, v26
	v_exp_f32_e32 v32, v32
	v_exp_f32_e32 v33, v33
	v_mul_f32_e32 v39, 0x3f4c422a, v39
	v_mul_f32_e32 v39, 0xc038aa3b, v39
	v_pk_mul_f32 v[16:17], v[16:17], v[40:41]
	v_exp_f32_e32 v40, v39
	v_mul_f32_e32 v39, 0x3d372713, v27
	v_mul_f32_e32 v39, v27, v39
	v_add_f32_e32 v32, 1.0, v32
	v_add_f32_e32 v33, 1.0, v33
	v_fma_f32 v39, v27, v39, v27
	v_rcp_f32_e32 v32, v32
	v_rcp_f32_e32 v33, v33
	v_mul_f32_e32 v39, 0x3f4c422a, v39
	v_mul_f32_e32 v39, 0xc038aa3b, v39
	v_exp_f32_e32 v41, v39
	v_pk_mul_f32 v[28:29], v[28:29], v[32:33]
	v_pk_mul_f32 v[32:33], v[24:25], v[24:25]
	v_rcp_f32_e32 v39, v37
	v_pk_fma_f32 v[32:33], v[28:29], v[28:29], v[32:33]
	v_add_f32_e32 v37, 1.0, v40
	v_pk_fma_f32 v[32:33], v[20:21], v[20:21], v[32:33]
	v_rcp_f32_e32 v40, v37
	v_add_f32_e32 v37, 1.0, v41
	v_pk_mul_f32 v[22:23], v[22:23], v[34:35]
	v_pk_fma_f32 v[32:33], v[16:17], v[16:17], v[32:33]
	v_rcp_f32_e32 v41, v37
	v_mul_f32_e32 v37, 0x3d372713, v22
	ds_bpermute_b32 v36, v141, v32
	v_pk_mul_f32 v[30:31], v[30:31], v[38:39]
	v_mul_f32_e32 v37, v22, v37
	v_mul_f32_e32 v38, 0x3d372713, v23
	v_pk_mul_f32 v[18:19], v[18:19], v[34:35]
	v_fma_f32 v37, v22, v37, v22
	v_mul_f32_e32 v38, v23, v38
	v_mul_f32_e32 v34, 0x3d372713, v18
	v_mul_f32_e32 v35, 0x3d372713, v19
	v_mul_f32_e32 v37, 0x3f4c422a, v37
	v_fma_f32 v38, v23, v38, v23
	v_mul_f32_e32 v34, v18, v34
	v_mul_f32_e32 v35, v19, v35
	v_mul_f32_e32 v37, 0xc038aa3b, v37
	v_mul_f32_e32 v38, 0x3f4c422a, v38
	v_fma_f32 v34, v18, v34, v18
	v_fma_f32 v35, v19, v35, v19
	v_exp_f32_e32 v37, v37
	v_mul_f32_e32 v38, 0xc038aa3b, v38
	v_mul_f32_e32 v34, 0x3f4c422a, v34
	v_mul_f32_e32 v35, 0x3f4c422a, v35
	s_waitcnt lgkmcnt(0)
	v_add_f32_e32 v32, v32, v36
	v_pk_mul_f32 v[26:27], v[26:27], v[40:41]
	v_exp_f32_e32 v41, v38
	v_mul_f32_e32 v34, 0xc038aa3b, v34
	v_mul_f32_e32 v35, 0xc038aa3b, v35
	ds_bpermute_b32 v36, v140, v32
	v_exp_f32_e32 v34, v34
	v_exp_f32_e32 v35, v35
	v_add_f32_e32 v37, 1.0, v37
	v_rcp_f32_e32 v40, v37
	v_add_f32_e32 v37, 1.0, v41
	v_rcp_f32_e32 v41, v37
	v_add_f32_e32 v34, 1.0, v34
	v_add_f32_e32 v35, 1.0, v35
	s_waitcnt lgkmcnt(0)
	v_add_f32_e32 v32, v32, v36
	v_rcp_f32_e32 v34, v34
	v_rcp_f32_e32 v35, v35
	ds_bpermute_b32 v36, v139, v32
	v_pk_mul_f32 v[38:39], v[26:27], v[26:27]
	v_pk_mul_f32 v[22:23], v[22:23], v[40:41]
	v_pk_fma_f32 v[38:39], v[30:31], v[30:31], v[38:39]
	v_pk_mul_f32 v[18:19], v[18:19], v[34:35]
	v_pk_fma_f32 v[38:39], v[22:23], v[22:23], v[38:39]
	s_waitcnt lgkmcnt(0)
	v_add_f32_e32 v36, v32, v36
	v_pk_fma_f32 v[38:39], v[18:19], v[18:19], v[38:39]
	ds_bpermute_b32 v32, v141, v33
	ds_bpermute_b32 v35, v141, v38
	ds_bpermute_b32 v37, v141, v39
	ds_bpermute_b32 v34, v138, v36
	s_waitcnt lgkmcnt(3)
	v_add_f32_e32 v32, v33, v32
	s_waitcnt lgkmcnt(2)
	v_add_f32_e32 v35, v38, v35
	s_waitcnt lgkmcnt(1)
	v_add_f32_e32 v37, v39, v37
	ds_bpermute_b32 v33, v140, v32
	ds_bpermute_b32 v38, v140, v35
	ds_bpermute_b32 v39, v140, v37
	s_waitcnt lgkmcnt(2)
	v_add_f32_e32 v32, v32, v33
	s_waitcnt lgkmcnt(1)
	v_add_f32_e32 v38, v35, v38
	s_waitcnt lgkmcnt(0)
	v_add_f32_e32 v41, v37, v39
	ds_bpermute_b32 v33, v139, v32
	ds_bpermute_b32 v40, v139, v38
	ds_bpermute_b32 v42, v139, v41
	s_waitcnt lgkmcnt(2)
	v_add_f32_e32 v35, v32, v33
	s_waitcnt lgkmcnt(1)
	v_add_f32_e32 v38, v38, v40
	s_waitcnt lgkmcnt(0)
	v_add_f32_e32 v40, v41, v42
	ds_bpermute_b32 v37, v138, v35
	ds_bpermute_b32 v39, v138, v38
	ds_bpermute_b32 v41, v138, v40
	v_add_u32_e32 v32, 0x60, v132
	v_ashrrev_i32_e32 v33, 31, v32
	s_and_saveexec_b64 s[6:7], vcc
	s_cbranch_execz .LBB0_195
	s_waitcnt lgkmcnt(2)
	v_add_f32_e32 v37, v35, v37
	v_add_f32_e32 v36, v36, v34
	v_lshl_add_u64 v[34:35], v[32:33], 2, s[16:17]
	s_waitcnt lgkmcnt(0)
	v_add_f32_e32 v40, v40, v41
	v_add_f32_e32 v38, v38, v39
	global_atomic_add_f32 v[34:35], v36, off
	global_atomic_add_f32 v[116:117], v37, off offset:388
	global_atomic_add_f32 v[116:117], v38, off offset:392
	global_atomic_add_f32 v[116:117], v40, off offset:396
; template <int EPI>
; __device__ __forceinline__ void gemm_tile(const Params& p, const u16* __restrict__ A, int lda, const u16* __restrict__ Bt, int ldb,
;                                           int K, int brow, int bcol, bool prefetched, int nbrow, int nbcol, char* shm) {
;     ...
;     for (int m = 0; m < 8; ++m) {
;       const int rowb = row0 + m * 16; float g[4][4], s4[4];
; #pragma unroll
;       for (int j = 0; j < 4; ++j) {
;         const float r1 = rstd1[rowb + j]; float s = 0.f;
; #pragma unroll
;         for (int n = 0; n < 4; ++n) { g[n][j] = gelu_tanh(acc[m][n][j] * r1); s += g[n][j] * g[n][j]; }
;     ...
; #pragma unroll
;       for (int n = 0; n < 4; ++n) {
;         u32x2 w = {cvtpk(g[n][0], g[n][1]), cvtpk(g[n][2], g[n][3])};
;         *(u32x2*)(dst + (long)(rowb >> 7) * 131072 + (long)(cb + n * 16 + fr) * 128 + (rowb & 127)) = w;
;       }
.LBB0_195:
	s_or_b64 exec, exec, s[6:7]
	v_ashrrev_i32_e32 v34, 7, v32
	v_ashrrev_i32_e32 v35, 31, v34
	v_lshlrev_b64 v[34:35], 18, v[34:35]
	v_and_b32_e32 v32, 0x7f, v32
	v_lshl_add_u64 v[34:35], s[14:15], 0, v[34:35]
	v_lshlrev_b32_e32 v204, 1, v32
	v_lshl_add_u64 v[32:33], v[34:35], 0, v[204:205]
	v_cvt_pk_bf16_f32 v28, v28, v29
	v_cvt_pk_bf16_f32 v29, v30, v31
	v_lshl_add_u64 v[30:31], v[32:33], 0, v[118:119]
	v_cvt_pk_bf16_f32 v24, v24, v25
	v_cvt_pk_bf16_f32 v25, v26, v27
	v_lshl_add_u64 v[26:27], v[32:33], 0, v[120:121]
	v_cvt_pk_bf16_f32 v20, v20, v21
	v_cvt_pk_bf16_f32 v21, v22, v23
	v_lshl_add_u64 v[22:23], v[32:33], 0, v[122:123]
	v_cvt_pk_bf16_f32 v16, v16, v17
	v_cvt_pk_bf16_f32 v17, v18, v19
	v_lshl_add_u64 v[18:19], v[32:33], 0, v[124:125]
	global_store_dwordx2 v[30:31], v[28:29], off
	global_store_dwordx2 v[26:27], v[24:25], off
	global_store_dwordx2 v[22:23], v[20:21], off
	global_store_dwordx2 v[18:19], v[16:17], off
	s_nop 1
	v_mov_b64_e32 v[16:17], v[240:241]
	v_mov_b64_e32 v[18:19], v[242:243]
	v_pk_mul_f32 v[8:9], v[8:9], v[16:17]
	v_pk_mul_f32 v[4:5], v[4:5], v[16:17]
	v_mul_f32_e32 v20, 0x3d372713, v8
	v_mul_f32_e32 v21, 0x3d372713, v9
	v_mul_f32_e32 v22, 0x3d372713, v4
	v_mul_f32_e32 v23, 0x3d372713, v5
	v_mul_f32_e32 v20, v8, v20
	v_mul_f32_e32 v21, v9, v21
	v_mul_f32_e32 v22, v4, v22
	v_mul_f32_e32 v23, v5, v23
	v_fma_f32 v20, v8, v20, v8
	v_fma_f32 v21, v9, v21, v9
	v_fma_f32 v22, v4, v22, v4
	v_fma_f32 v23, v5, v23, v5
	v_mul_f32_e32 v20, 0x3f4c422a, v20
	v_mul_f32_e32 v21, 0x3f4c422a, v21
	v_mul_f32_e32 v22, 0x3f4c422a, v22
	v_mul_f32_e32 v23, 0x3f4c422a, v23
	v_mul_f32_e32 v20, 0xc038aa3b, v20
	v_mul_f32_e32 v21, 0xc038aa3b, v21
	v_mul_f32_e32 v22, 0xc038aa3b, v22
	v_mul_f32_e32 v23, 0xc038aa3b, v23
	v_exp_f32_e32 v20, v20
	v_exp_f32_e32 v21, v21
	v_exp_f32_e32 v22, v22
	v_exp_f32_e32 v23, v23
	v_add_f32_e32 v20, 1.0, v20
	v_add_f32_e32 v21, 1.0, v21
	v_pk_mul_f32 v[14:15], v[14:15], v[18:19]
	v_add_f32_e32 v22, 1.0, v22
	v_add_f32_e32 v23, 1.0, v23
	v_rcp_f32_e32 v20, v20
	v_rcp_f32_e32 v21, v21
	v_pk_mul_f32 v[0:1], v[0:1], v[16:17]
	v_mul_f32_e32 v26, 0x3d372713, v14
	v_rcp_f32_e32 v22, v22
	v_rcp_f32_e32 v23, v23
	v_mul_f32_e32 v24, 0x3d372713, v0
	v_mul_f32_e32 v25, 0x3d372713, v1
	v_mul_f32_e32 v27, 0x3d372713, v15
	v_mul_f32_e32 v26, v14, v26
	v_mul_f32_e32 v24, v0, v24
	v_mul_f32_e32 v25, v1, v25
	v_mul_f32_e32 v27, v15, v27
	v_fma_f32 v26, v14, v26, v14
	v_fma_f32 v24, v0, v24, v0
	v_fma_f32 v25, v1, v25, v1
	v_fma_f32 v27, v15, v27, v15
	v_pk_mul_f32 v[8:9], v[8:9], v[20:21]
	v_mul_f32_e32 v21, 0x3f4c422a, v26
	v_mul_f32_e32 v24, 0x3f4c422a, v24
	v_mul_f32_e32 v25, 0x3f4c422a, v25
	v_pk_mul_f32 v[4:5], v[4:5], v[22:23]
	v_mul_f32_e32 v22, 0x3f4c422a, v27
	v_mul_f32_e32 v21, 0xc038aa3b, v21
	v_mul_f32_e32 v24, 0xc038aa3b, v24
	v_mul_f32_e32 v25, 0xc038aa3b, v25
	v_exp_f32_e32 v21, v21
	v_mul_f32_e32 v22, 0xc038aa3b, v22
	v_exp_f32_e32 v24, v24
	v_exp_f32_e32 v25, v25
	v_exp_f32_e32 v23, v22
	v_pk_mul_f32 v[12:13], v[12:13], v[16:17]
	v_add_f32_e32 v21, 1.0, v21
	v_mul_f32_e32 v16, 0x3d372713, v12
	v_mul_f32_e32 v17, 0x3d372713, v13
	v_mul_f32_e32 v16, v12, v16
	v_mul_f32_e32 v17, v13, v17
	v_pk_mul_f32 v[10:11], v[10:11], v[18:19]
	v_fma_f32 v16, v12, v16, v12
	v_fma_f32 v17, v13, v17, v13
	v_add_f32_e32 v24, 1.0, v24
	v_add_f32_e32 v25, 1.0, v25
	v_rcp_f32_e32 v22, v21
	v_add_f32_e32 v21, 1.0, v23
	v_mul_f32_e32 v23, 0x3d372713, v10
	v_mul_f32_e32 v16, 0x3f4c422a, v16
	v_mul_f32_e32 v17, 0x3f4c422a, v17
	v_rcp_f32_e32 v24, v24
	v_rcp_f32_e32 v25, v25
	v_mul_f32_e32 v23, v10, v23
	v_mul_f32_e32 v16, 0xc038aa3b, v16
	v_mul_f32_e32 v17, 0xc038aa3b, v17
	v_fma_f32 v23, v10, v23, v10
	v_exp_f32_e32 v16, v16
	v_exp_f32_e32 v17, v17
	v_mul_f32_e32 v23, 0x3f4c422a, v23
	v_mul_f32_e32 v23, 0xc038aa3b, v23
	v_pk_mul_f32 v[0:1], v[0:1], v[24:25]
	v_exp_f32_e32 v24, v23
	v_mul_f32_e32 v23, 0x3d372713, v11
	v_mul_f32_e32 v23, v11, v23
	v_add_f32_e32 v16, 1.0, v16
	v_add_f32_e32 v17, 1.0, v17
	v_fma_f32 v23, v11, v23, v11
	v_rcp_f32_e32 v16, v16
	v_rcp_f32_e32 v17, v17
	v_mul_f32_e32 v23, 0x3f4c422a, v23
	v_mul_f32_e32 v23, 0xc038aa3b, v23
	v_exp_f32_e32 v25, v23
	v_pk_mul_f32 v[12:13], v[12:13], v[16:17]
	v_pk_mul_f32 v[16:17], v[8:9], v[8:9]
	v_rcp_f32_e32 v23, v21
	v_pk_fma_f32 v[16:17], v[12:13], v[12:13], v[16:17]
	v_add_f32_e32 v21, 1.0, v24
	v_pk_fma_f32 v[16:17], v[4:5], v[4:5], v[16:17]
	v_rcp_f32_e32 v24, v21
	v_add_f32_e32 v21, 1.0, v25
	v_pk_mul_f32 v[6:7], v[6:7], v[18:19]
	v_pk_fma_f32 v[16:17], v[0:1], v[0:1], v[16:17]
	v_rcp_f32_e32 v25, v21
	v_mul_f32_e32 v21, 0x3d372713, v6
	ds_bpermute_b32 v20, v141, v16
	v_pk_mul_f32 v[14:15], v[14:15], v[22:23]
	v_mul_f32_e32 v21, v6, v21
	v_mul_f32_e32 v22, 0x3d372713, v7
	v_pk_mul_f32 v[2:3], v[2:3], v[18:19]
	v_fma_f32 v21, v6, v21, v6
	v_mul_f32_e32 v22, v7, v22
	v_mul_f32_e32 v18, 0x3d372713, v2
	v_mul_f32_e32 v19, 0x3d372713, v3
	v_mul_f32_e32 v21, 0x3f4c422a, v21
	v_fma_f32 v22, v7, v22, v7
	v_mul_f32_e32 v18, v2, v18
	v_mul_f32_e32 v19, v3, v19
	v_mul_f32_e32 v21, 0xc038aa3b, v21
	v_mul_f32_e32 v22, 0x3f4c422a, v22
	v_fma_f32 v18, v2, v18, v2
	v_fma_f32 v19, v3, v19, v3
	v_exp_f32_e32 v21, v21
	v_mul_f32_e32 v22, 0xc038aa3b, v22
	v_mul_f32_e32 v18, 0x3f4c422a, v18
	v_mul_f32_e32 v19, 0x3f4c422a, v19
	s_waitcnt lgkmcnt(0)
; template <int EPI>
; __device__ __forceinline__ void gemm_tile(const Params& p, const u16* __restrict__ A, int lda, const u16* __restrict__ Bt, int ldb,
;                                           int K, int brow, int bcol, bool prefetched, int nbrow, int nbcol, char* shm) {
;     ...
;         s4[j] = red16(s);
;       }
;       if (fr == 0) {
; #pragma unroll
;         for (int j = 0; j < 4; ++j) unsafeAtomicAdd(&ssq[rowb + j], s4[j]);
	v_add_f32_e32 v16, v16, v20
	v_pk_mul_f32 v[10:11], v[10:11], v[24:25]
	v_exp_f32_e32 v25, v22
	v_mul_f32_e32 v18, 0xc038aa3b, v18
	v_mul_f32_e32 v19, 0xc038aa3b, v19
	ds_bpermute_b32 v20, v140, v16
	v_exp_f32_e32 v18, v18
	v_exp_f32_e32 v19, v19
	v_add_f32_e32 v21, 1.0, v21
	v_rcp_f32_e32 v24, v21
	v_add_f32_e32 v21, 1.0, v25
	v_rcp_f32_e32 v25, v21
	v_add_f32_e32 v18, 1.0, v18
	v_add_f32_e32 v19, 1.0, v19
	s_waitcnt lgkmcnt(0)
	v_add_f32_e32 v16, v16, v20
	v_rcp_f32_e32 v18, v18
	v_rcp_f32_e32 v19, v19
	ds_bpermute_b32 v20, v139, v16
	v_pk_mul_f32 v[22:23], v[10:11], v[10:11]
	v_pk_mul_f32 v[6:7], v[6:7], v[24:25]
	v_pk_fma_f32 v[22:23], v[14:15], v[14:15], v[22:23]
	v_pk_mul_f32 v[2:3], v[2:3], v[18:19]
	v_pk_fma_f32 v[22:23], v[6:7], v[6:7], v[22:23]
	s_waitcnt lgkmcnt(0)
	v_add_f32_e32 v20, v16, v20
	v_pk_fma_f32 v[22:23], v[2:3], v[2:3], v[22:23]
	ds_bpermute_b32 v16, v141, v17
	ds_bpermute_b32 v19, v141, v22
	ds_bpermute_b32 v21, v141, v23
	ds_bpermute_b32 v18, v138, v20
	s_waitcnt lgkmcnt(3)
	v_add_f32_e32 v16, v17, v16
	s_waitcnt lgkmcnt(2)
	v_add_f32_e32 v19, v22, v19
	s_waitcnt lgkmcnt(1)
	v_add_f32_e32 v21, v23, v21
	ds_bpermute_b32 v17, v140, v16
	ds_bpermute_b32 v22, v140, v19
	ds_bpermute_b32 v23, v140, v21
	s_waitcnt lgkmcnt(2)
	v_add_f32_e32 v16, v16, v17
	s_waitcnt lgkmcnt(1)
	v_add_f32_e32 v22, v19, v22
	s_waitcnt lgkmcnt(0)
	v_add_f32_e32 v25, v21, v23
	ds_bpermute_b32 v17, v139, v16
	ds_bpermute_b32 v24, v139, v22
	ds_bpermute_b32 v26, v139, v25
	s_waitcnt lgkmcnt(2)
	v_add_f32_e32 v19, v16, v17
	s_waitcnt lgkmcnt(1)
	v_add_f32_e32 v22, v22, v24
	s_waitcnt lgkmcnt(0)
	v_add_f32_e32 v24, v25, v26
	ds_bpermute_b32 v21, v138, v19
	ds_bpermute_b32 v23, v138, v22
	ds_bpermute_b32 v25, v138, v24
	v_add_u32_e32 v16, 0x70, v132
	v_ashrrev_i32_e32 v17, 31, v16
	s_and_saveexec_b64 s[6:7], vcc
	s_cbranch_execz .LBB0_95
	s_waitcnt lgkmcnt(2)
	v_add_f32_e32 v21, v19, v21
	v_add_f32_e32 v20, v20, v18
	v_lshl_add_u64 v[18:19], v[16:17], 2, s[16:17]
	s_waitcnt lgkmcnt(0)
	v_add_f32_e32 v24, v24, v25
	v_add_f32_e32 v22, v22, v23
	global_atomic_add_f32 v[18:19], v20, off
	global_atomic_add_f32 v[116:117], v21, off offset:452
	global_atomic_add_f32 v[116:117], v22, off offset:456
	global_atomic_add_f32 v[116:117], v24, off offset:460
	s_branch .LBB0_95
